# ret_out log2(gamma) short form; LRU gate-weight staging with 16 loads in flight
# speedup vs baseline: 1.0545x; 1.0016x over previous
; #define LAS __attribute__((address_space(3)))
; __device__ __forceinline__ void ret_prefetch(const Frame& F, int it, int nchu, RetPre& P) {
;     const int bh = it / nchu, mc = it - bh * nchu + (NCH - nchu), h = bh & 7, b = bh >> 3;
;     const int tid = F.tid;
;     const size_t rowbase = (size_t)b * TB + 128 * mc;
; #pragma unroll
;     for (int i = 0; i < 2; ++i) {
;         const int u = tid + i * NTHREADS, r = u >> 3, c8 = (u & 7) * 8;
;         P.k[i] = *(const u32x4*)(WSB(WS_KN) + (rowbase + r) * 512 + h * 64 + c8);
;         P.sf[i] = *(const u32x4*)(WSB(WS_ST) + ((((size_t)(b * NH + h) * 2 + 0) * NCH + mc) * DV + r) * DK + c8);
;         P.sb[i] = *(const u32x4*)(WSB(WS_ST) + ((((size_t)(b * NH + h) * 2 + 1) * NCH + mc) * DV + r) * DK + c8);
;     }
; #pragma unroll
;     for (int i = 0; i < 4; ++i) {
;         const int u = tid + i * NTHREADS, r = u >> 4, c8 = (u & 15) * 8;
;         P.vt[i] = *(const u32x4*)(WSB(WS_VT) + ((size_t)(b * NH + h) * DV + r) * TB + 128 * mc + c8);
;     }
; }
; __device__ __forceinline__ void ret_out_phase(const Args& A, Frame& F, int l, bool lastl, bf16_t* ARET, bf16_t* ALRU) {
;     ...
;     for (int jx = 0; jx < nmy; ++jx) {
;         const int it = F.bid + jx * F.G, itn = (jx + 1 < nmy) ? it + F.G : it;
;         const int bh = it / NCHU, mc = it - bh * NCHU + (NCH - NCHU), h = bh & 7, b = bh >> 3;
;         const size_t rowbase = (size_t)b * TB + 128 * mc;
;         __syncthreads();
; #pragma unroll
;         for (int i = 0; i < 2; ++i) {
;             const int u = tid + i * NTHREADS, r = u >> 3, c8 = (u & 7) * 8;
;             *(LAS u32x4*)(ks_ + r * 72 + c8) = P.k[i]; *(LAS u32x4*)(sfs + r * 72 + c8) = P.sf[i]; *(LAS u32x4*)(sbs + r * 72 + c8) = P.sb[i];
;         }
; #pragma unroll
;         for (int i = 0; i < 4; ++i) { const int u = tid + i * NTHREADS, r = u >> 4, c8 = (u & 15) * 8; *(LAS u32x4*)(vts + r * 136 + c8) = P.vt[i]; }
;         bf16x8 qf[2];
; #pragma unroll
;         for (int ks = 0; ks < 2; ++ks) qf[ks] = *(const bf16x8*)(WSB(WS_Q) + (rowbase + 16 * w + fr) * 512 + h * 64 + 32 * ks + 8 * fq);
;         __syncthreads();
;         ret_prefetch(F, itn, NCHU, P);
;         const float l2f = log2_gamma(A, F, l, 0, h), l2b = log2_gamma(A, F, l, 1, h);
.LBB0_30:
	s_add_i32 s39, s39, 1
	s_cmp_lt_i32 s39, s37
	s_cselect_b32 s2, s34, 0
	s_abs_i32 s5, vcc_hi
	s_mul_hi_u32 s8, s5, s45
	s_mul_i32 s9, s8, s20
	s_sub_i32 s5, s5, s9
	s_ashr_i32 s4, vcc_hi, 31
	s_add_i32 s9, s8, 1
	s_sub_i32 s25, s5, s20
	s_cmp_ge_u32 s5, s20
	s_cselect_b32 s8, s9, s8
	s_cselect_b32 s5, s25, s5
	s_add_i32 s9, s8, 1
	s_cmp_ge_u32 s5, s20
	s_cselect_b32 s5, s9, s8
	s_xor_b32 s5, s5, s4
	s_sub_i32 s4, s5, s4
	s_not_b32 s5, s4
	s_mul_i32 s5, vcc_lo, s5
	s_ashr_i32 s8, s4, 3
	s_add_i32 s5, s61, s5
	s_ashr_i32 s9, s5, 31
	s_add_i32 s25, s2, vcc_hi
	s_mul_hi_i32 s52, s8, 0x900
	s_mulk_i32 s8, 0x900
	s_and_b32 s2, s4, 7
	s_add_u32 s8, s8, s5
	s_addc_u32 s9, s52, s9
	s_abs_i32 s5, s25
	s_mul_hi_u32 s52, s5, s45
	s_mul_i32 s53, s52, s20
	s_sub_i32 s5, s5, s53
	s_lshl_b32 s82, s2, 7
	s_ashr_i32 s4, s25, 31
	s_add_i32 s53, s52, 1
	s_sub_i32 s58, s5, s20
	s_cmp_ge_u32 s5, s20
	s_cselect_b32 s52, s53, s52
	s_cselect_b32 s5, s58, s5
	s_add_i32 s53, s52, 1
	s_cmp_ge_u32 s5, s20
	s_cselect_b32 s5, s53, s52
	s_xor_b32 s5, s5, s4
	s_sub_i32 s4, s5, s4
	s_not_b32 s5, s4
	s_mul_i32 s5, s20, s5
	s_add_i32 s5, s25, s5
	v_lshl_add_u64 v[50:51], v[122:123], 0, s[8:9]
	v_lshlrev_b64 v[50:51], 10, v[50:51]
	v_lshl_add_u64 v[50:51], s[48:49], 0, v[50:51]
	v_lshl_add_u64 v[50:51], v[50:51], 0, s[82:83]
	v_lshl_add_u64 v[50:51], v[50:51], 0, v[0:1]
	global_load_dwordx4 v[46:49], v[50:51], off
	global_load_dwordx4 v[42:45], v[50:51], off offset:64
	s_barrier
	s_waitcnt vmcnt(0)
	ds_write_b128 v134, v[6:9]
	ds_write_b128 v134, v[10:13] offset:53248
	ds_write_b128 v135, v[2:5]
	ds_write_b128 v136, v[22:25]
	ds_write_b128 v136, v[26:29] offset:53248
	ds_write_b128 v137, v[34:37]
	v_lshl_add_u64 v[2:3], v[122:123], 0, s[8:9]
	s_add_i32 s25, s5, 18
	v_lshlrev_b64 v[2:3], 10, v[2:3]
	s_ashr_i32 s5, s4, 3
	s_lshl_b32 s72, s25, 7
	v_lshl_add_u64 v[2:3], s[48:49], 0, v[2:3]
	s_mul_hi_i32 s52, s5, 0x900
	s_mulk_i32 s5, 0x900
	s_ashr_i32 s73, s72, 31
	v_lshl_add_u64 v[2:3], v[2:3], 0, s[82:83]
	s_add_u32 s92, s5, s72
	ds_write_b128 v245, v[14:17] offset:18432
	ds_write_b128 v246, v[18:21] offset:18432
	ds_write_b128 v247, v[30:33] offset:18432
	ds_write_b128 v248, v[38:41] offset:18432
	v_lshl_add_u64 v[2:3], v[2:3], 0, v[0:1]
	s_addc_u32 s93, s52, s73
	s_ashr_i32 s5, s4, 31
	s_mul_i32 s52, s4, 36
	s_ashr_i32 s58, s25, 31
	s_mul_hi_i32 s53, s4, 36
	s_add_u32 s52, s52, s25
	v_lshl_add_u64 v[2:3], s[92:93], 0, v[116:117]
	v_lshl_add_u64 v[14:15], s[92:93], 0, v[114:115]
	s_addc_u32 s53, s53, s58
	v_lshlrev_b64 v[2:3], 10, v[2:3]
	s_lshl_b32 s25, s4, 7
	v_lshlrev_b64 v[14:15], 10, v[14:15]
	s_lshl_b64 s[52:53], s[52:53], 14
	v_lshl_add_u64 v[2:3], s[6:7], 0, v[2:3]
	s_and_b32 s78, s25, 0x380
	s_mov_b32 s79, s83
	v_lshl_add_u64 v[14:15], s[6:7], 0, v[14:15]
	v_lshl_add_u64 v[2:3], v[2:3], 0, s[78:79]
	v_mov_b32_e32 v129, v1
	s_add_u32 s76, s62, s52
	v_lshl_add_u64 v[14:15], v[14:15], 0, s[78:79]
	v_lshl_add_u64 v[2:3], v[2:3], 0, v[128:129]
	s_addc_u32 s77, s63, s53
	v_lshl_add_u64 v[14:15], v[14:15], 0, v[128:129]
	s_waitcnt lgkmcnt(0)
	s_barrier
	global_load_dwordx4 v[6:9], v[2:3], off
	global_load_dwordx4 v[22:25], v[14:15], off
	v_lshl_add_u64 v[2:3], s[76:77], 0, v[120:121]
	s_add_u32 s74, s65, s52
	v_lshl_add_u64 v[14:15], s[76:77], 0, v[118:119]
	v_lshl_add_u64 v[2:3], v[2:3], 0, v[128:129]
	s_addc_u32 s75, s19, s53
	v_lshl_add_u64 v[14:15], v[14:15], 0, v[128:129]
	global_load_dwordx4 v[10:13], v[2:3], off
	global_load_dwordx4 v[26:29], v[14:15], off
	v_lshl_add_u64 v[2:3], s[74:75], 0, v[120:121]
	v_lshl_add_u64 v[14:15], s[74:75], 0, v[118:119]
	v_lshl_add_u64 v[2:3], v[2:3], 0, v[128:129]
	v_lshl_add_u64 v[14:15], v[14:15], 0, v[128:129]
	s_lshl_b64 s[74:75], s[4:5], 7
	global_load_dwordx4 v[2:5], v[2:3], off
	v_mov_b64_e32 v[38:39], s[54:55]
	global_load_dwordx4 v[34:37], v[14:15], off
	v_lshl_add_u64 v[14:15], s[74:75], 0, v[106:107]
	v_lshl_add_u64 v[18:19], s[74:75], 0, v[108:109]
	v_lshl_add_u64 v[30:31], s[74:75], 0, v[110:111]
	v_lshl_add_u64 v[50:51], s[74:75], 0, v[112:113]
	v_mad_u64_u32 v[16:17], s[4:5], v14, s96, v[38:39]
	v_mad_u64_u32 v[20:21], s[52:53], v18, s96, v[38:39]
	v_mad_u64_u32 v[32:33], s[52:53], v30, s96, v[38:39]
	v_mad_u64_u32 v[38:39], s[52:53], v50, s96, v[38:39]
	s_load_dwordx2 s[74:75], s[46:47], 0x60
	v_mad_i32_i24 v17, v15, s96, v17
	s_lshl_b64 s[4:5], s[72:73], 1
	v_mad_i32_i24 v21, v19, s96, v21
	v_mad_i32_i24 v33, v31, s96, v33
	v_mad_i32_i24 v39, v51, s96, v39
	v_lshl_add_u64 v[14:15], v[16:17], 0, s[4:5]
	v_lshl_add_u64 v[18:19], v[20:21], 0, s[4:5]
	v_lshl_add_u64 v[30:31], v[32:33], 0, s[4:5]
	v_lshl_add_u64 v[38:39], v[38:39], 0, s[4:5]
	s_or_b32 s4, s2, s64
	s_ashr_i32 s5, s4, 31
	s_lshl_b64 s[4:5], s[4:5], 2
	s_waitcnt lgkmcnt(0)
	s_add_u32 s78, s74, s4
	s_addc_u32 s79, s75, s5
	s_load_dword s98, s[78:79], 0x0
	s_load_dword s99, s[78:79], 0x20
	s_mov_b32 s76, 0xb2a5705f
	s_mov_b32 s77, 0x42ce8ed0
	s_mov_b32 s58, 0xc2b17218
	s_mov_b32 s25, 0x3f2aaaab
	s_mov_b32 s72, 0x7f800000
	s_mov_b32 s73, 0x33800000
	v_lshlrev_b32_e32 v40, 1, v104
	v_mov_b32_e32 v41, v1
	v_lshl_add_u64 v[14:15], v[14:15], 0, v[40:41]
	v_lshl_add_u64 v[18:19], v[18:19], 0, v[40:41]
	v_lshl_add_u64 v[30:31], v[30:31], 0, v[40:41]
	v_lshl_add_u64 v[38:39], v[38:39], 0, v[40:41]
	global_load_dwordx4 v[14:17], v[14:15], off
	v_readlane_b32 s4, v254, 38
	global_load_dwordx4 v[18:21], v[18:19], off
	v_readlane_b32 s5, v254, 39
	global_load_dwordx4 v[30:33], v[30:31], off
	v_add_u32_e32 v82, 0x4800, v230
	global_load_dwordx4 v[38:41], v[38:39], off
	s_mov_b32 s53, s64
	s_waitcnt vmcnt(10) lgkmcnt(0)
; #define LAS __attribute__((address_space(3)))
; __device__ __forceinline__ unsigned pk2(float lo, float hi) { const f32x2_t v = {lo, hi}; const bf16v2_t b = __builtin_convertvector(v, bf16v2_t); return __builtin_bit_cast(unsigned, b); }
; __device__ __forceinline__ float softplusf_(float x) { return fmaxf(x, 0.f) + log1pf(expf(-fabsf(x))); }
; __device__ __forceinline__ float log2_gamma(const Args& A, const Frame& F, int l, int dir, int h) {
;     const float x = GIN(12)[(l * 2 + dir) * NH + h];
;     return -softplusf_(-x) * 1.4426950408889634f;
; }
; __device__ __forceinline__ void ret_out_phase(const Args& A, Frame& F, int l, bool lastl, bf16_t* ARET, bf16_t* ALRU) {
;     ...
;         const float l2f = log2_gamma(A, F, l, 0, h), l2b = log2_gamma(A, F, l, 1, h);
;         bf16x8 pa[4];
;         {
;             const int i_loc = 16 * w + fr;
; #pragma unroll
;             for (int jp = 0; jp < 4; ++jp) {
;                 f32x4 c0 = (f32x4){0.f, 0.f, 0.f, 0.f}, c1 = c0;
; #pragma unroll
;                 for (int ks = 0; ks < 2; ++ks) {
;                     const bf16x8 k0 = *(const LAS bf16x8*)(ks_ + (32 * jp + fr) * 72 + 32 * ks + 8 * fq);
;                     const bf16x8 k1 = *(const LAS bf16x8*)(ks_ + (32 * jp + 16 + fr) * 72 + 32 * ks + 8 * fq);
;                     c0 = __builtin_amdgcn_mfma_f32_16x16x32_bf16(k0, qf[ks], c0, 0, 0, 0);
;                     c1 = __builtin_amdgcn_mfma_f32_16x16x32_bf16(k1, qf[ks], c1, 0, 0, 0);
;                 }
;                 float v[8];
; #pragma unroll
;                 for (int r = 0; r < 4; ++r) {
;                     const int j0 = 32 * jp + 4 * fq + r, j1 = j0 + 16;
;                     const int d0 = i_loc - j0, d1 = i_loc - j1;
;                     v[r] = c0[r] * (d0 >= 0 ? exp2f((float)d0 * l2f) : exp2f((float)(-d0) * l2b));
;                     v[4 + r] = c1[r] * (d1 >= 0 ? exp2f((float)d1 * l2f) : exp2f((float)(-d1) * l2b));
;                 }
;                 u32x4 pv; pv[0] = pk2(v[0], v[1]); pv[1] = pk2(v[2], v[3]); pv[2] = pk2(v[4], v[5]); pv[3] = pk2(v[6], v[7]);
;                 pa[jp] = __builtin_bit_cast(bf16x8, pv);
;             }
	s_mov_b32 s100, 0x3c800000
	v_mov_b32_e32 v50, s98
	v_and_b32_e32 v51, 0x7fffffff, v50
	v_mul_f32_e32 v51, 0xbfb8aa3b, v51
	v_exp_f32_e32 v51, v51
	v_mov_b32_e32 v52, 0x3e4ccccd
	v_fmaak_f32 v52, v51, v52, 0xbe800000
	v_fmaak_f32 v52, v51, v52, 0x3eaaaaab
	v_fmaak_f32 v52, v51, v52, 0xbf000000
	v_fmaak_f32 v52, v51, v52, 0x3f800000
	v_mul_f32_e32 v52, v51, v52
	v_add_f32_e32 v53, 1.0, v51
	v_log_f32_e32 v53, v53
	v_cmp_gt_f32_e64 s[74:75], s100, v51
	v_mul_f32_e32 v53, 0x3f317218, v53
	s_nop 1
	v_cndmask_b32_e64 v52, v53, v52, s[74:75]
	v_max_f32_e64 v53, -v50, 0
	v_add_f32_e32 v52, v53, v52
	v_mul_f32_e32 v66, 0xbfb8aa3b, v52
	v_mov_b32_e32 v54, s99
	v_and_b32_e32 v55, 0x7fffffff, v54
	v_mul_f32_e32 v55, 0xbfb8aa3b, v55
	v_exp_f32_e32 v55, v55
	v_mov_b32_e32 v56, 0x3e4ccccd
	v_fmaak_f32 v56, v55, v56, 0xbe800000
	v_fmaak_f32 v56, v55, v56, 0x3eaaaaab
	v_fmaak_f32 v56, v55, v56, 0xbf000000
	v_fmaak_f32 v56, v55, v56, 0x3f800000
	v_mul_f32_e32 v56, v55, v56
	v_add_f32_e32 v57, 1.0, v55
	v_log_f32_e32 v57, v57
	v_cmp_gt_f32_e64 s[74:75], s100, v55
	v_mul_f32_e32 v57, 0x3f317218, v57
	s_nop 1
	v_cndmask_b32_e64 v56, v57, v56, s[74:75]
	v_max_f32_e64 v57, -v54, 0
	v_add_f32_e32 v56, v57, v56
	v_mul_f32_e32 v67, 0xbfb8aa3b, v56
	ds_read_b128 v[50:53], v143
	ds_read_b128 v[54:57], v143 offset:2304
	s_waitcnt lgkmcnt(1)
	v_mfma_f32_16x16x32_bf16 v[50:53], v[50:53], v[46:49], 0
	ds_read_b128 v[58:61], v143 offset:64
	ds_read_b128 v[62:65], v143 offset:2368
	s_waitcnt lgkmcnt(1)
	v_mfma_f32_16x16x32_bf16 v[50:53], v[58:61], v[42:45], v[50:53]
	v_mul_f32_e32 v58, v67, v144
	v_mul_f32_e32 v59, v66, v145
	v_cndmask_b32_e64 v58, v59, v58, s[4:5]
	v_cmp_gt_f32_e64 s[74:75], s3, v58
	v_readlane_b32 s4, v254, 36
	v_mul_f32_e32 v60, v66, v147
	v_cndmask_b32_e64 v59, 0, v183, s[74:75]
	v_add_f32_e32 v58, v58, v59
	v_exp_f32_e32 v58, v58
	v_cndmask_b32_e64 v59, 0, v184, s[74:75]
	v_readlane_b32 s5, v254, 37
	v_mul_f32_e32 v61, v67, v148
	v_ldexp_f32 v58, v58, v59
	v_mul_f32_e32 v59, v67, v146
	v_cndmask_b32_e64 v59, v60, v59, s[4:5]
	v_cmp_gt_f32_e64 s[74:75], s3, v59
	v_readlane_b32 s4, v254, 40
	v_readlane_b32 s5, v254, 41
	v_cndmask_b32_e64 v60, 0, v183, s[74:75]
	v_add_f32_e32 v59, v59, v60
	v_exp_f32_e32 v59, v59
	v_cndmask_b32_e64 v60, 0, v184, s[74:75]
	v_mfma_f32_16x16x32_bf16 v[54:57], v[54:57], v[46:49], 0
	v_ldexp_f32 v60, v59, v60
	v_mul_f32_e32 v59, v66, v149
	v_cndmask_b32_e64 v59, v59, v61, s[4:5]
	v_cmp_gt_f32_e64 s[74:75], s3, v59
	v_readlane_b32 s4, v254, 42
	v_readlane_b32 s5, v254, 43
	v_cndmask_b32_e64 v61, 0, v183, s[74:75]
	v_add_f32_e32 v59, v59, v61
	v_exp_f32_e32 v59, v59
	v_cndmask_b32_e64 v61, 0, v184, s[74:75]
	s_waitcnt lgkmcnt(0)
	v_mfma_f32_16x16x32_bf16 v[54:57], v[62:65], v[42:45], v[54:57]
	v_ldexp_f32 v59, v59, v61
	v_pk_mul_f32 v[50:51], v[50:51], v[58:59]
	v_mul_f32_e32 v58, v66, v151
	v_mul_f32_e32 v59, v67, v150
	v_cndmask_b32_e64 v58, v58, v59, s[4:5]
	v_cmp_gt_f32_e64 s[74:75], s3, v58
	v_readlane_b32 s4, v254, 44
	v_readlane_b32 s5, v254, 45
	v_cndmask_b32_e64 v59, 0, v183, s[74:75]
	v_add_f32_e32 v58, v58, v59
	v_exp_f32_e32 v58, v58
	v_cndmask_b32_e64 v59, 0, v184, s[74:75]
	v_cvt_pk_bf16_f32 v50, v50, v51
	v_ldexp_f32 v61, v58, v59
	v_mul_f32_e32 v58, v66, v153
	v_mul_f32_e32 v59, v67, v152
	v_cndmask_b32_e64 v58, v58, v59, s[4:5]
	v_cmp_gt_f32_e64 s[74:75], s3, v58
	v_readlane_b32 s4, v254, 46
	v_pk_mul_f32 v[54:55], v[54:55], v[60:61]
	v_cndmask_b32_e64 v59, 0, v183, s[74:75]
	v_add_f32_e32 v58, v58, v59
	v_exp_f32_e32 v58, v58
	v_cndmask_b32_e64 v59, 0, v184, s[74:75]
	v_mul_f32_e32 v60, v67, v154
	v_readlane_b32 s5, v254, 47
	v_ldexp_f32 v58, v58, v59
	v_mul_f32_e32 v59, v66, v155
	v_cndmask_b32_e64 v59, v59, v60, s[4:5]
	v_cmp_gt_f32_e64 s[74:75], s3, v59
	v_readlane_b32 s4, v254, 48
	v_mul_f32_e32 v61, v67, v156
	v_cndmask_b32_e64 v60, 0, v183, s[74:75]
	v_add_f32_e32 v59, v59, v60
	v_exp_f32_e32 v59, v59
	v_cndmask_b32_e64 v60, 0, v184, s[74:75]
	v_readlane_b32 s5, v254, 49
	v_ldexp_f32 v60, v59, v60
	v_mul_f32_e32 v59, v66, v157
	v_cndmask_b32_e64 v59, v59, v61, s[4:5]
	v_cmp_gt_f32_e64 s[74:75], s3, v59
	v_readlane_b32 s4, v254, 50
	v_readlane_b32 s5, v254, 51
	v_cndmask_b32_e64 v61, 0, v183, s[74:75]
	v_add_f32_e32 v59, v59, v61
	v_exp_f32_e32 v59, v59
	v_cndmask_b32_e64 v61, 0, v184, s[74:75]
	v_ldexp_f32 v59, v59, v61
	v_pk_mul_f32 v[52:53], v[52:53], v[58:59]
	v_mul_f32_e32 v58, v66, v159
	v_mul_f32_e32 v59, v67, v158
	v_cndmask_b32_e64 v58, v58, v59, s[4:5]
	v_cmp_gt_f32_e64 s[74:75], s3, v58
	v_cvt_pk_bf16_f32 v51, v52, v53
	v_cvt_pk_bf16_f32 v52, v54, v55
	v_cndmask_b32_e64 v59, 0, v183, s[74:75]
	v_add_f32_e32 v58, v58, v59
	v_exp_f32_e32 v58, v58
	v_cndmask_b32_e64 v59, 0, v184, s[74:75]
	v_readlane_b32 s4, v254, 52
	v_readlane_b32 s5, v254, 53
	v_ldexp_f32 v61, v58, v59
	v_pk_mul_f32 v[56:57], v[56:57], v[60:61]
	s_nop 0
	v_cvt_pk_bf16_f32 v53, v56, v57
	ds_read_b128 v[54:57], v160
	ds_read_b128 v[58:61], v160 offset:2304
	s_waitcnt lgkmcnt(1)
	v_mfma_f32_16x16x32_bf16 v[54:57], v[54:57], v[46:49], 0
	ds_read_b128 v[62:65], v160 offset:64
	ds_read_b128 v[68:71], v160 offset:2368
	s_waitcnt lgkmcnt(1)
; #define LAS __attribute__((address_space(3)))
; __device__ __forceinline__ unsigned pk2(float lo, float hi) { const f32x2_t v = {lo, hi}; const bf16v2_t b = __builtin_convertvector(v, bf16v2_t); return __builtin_bit_cast(unsigned, b); }
; __device__ __forceinline__ void ret_out_phase(const Args& A, Frame& F, int l, bool lastl, bf16_t* ARET, bf16_t* ALRU) {
;     ...
;         bf16x8 pa[4];
;         {
;             const int i_loc = 16 * w + fr;
; #pragma unroll
;             for (int jp = 0; jp < 4; ++jp) {
;                 f32x4 c0 = (f32x4){0.f, 0.f, 0.f, 0.f}, c1 = c0;
; #pragma unroll
;                 for (int ks = 0; ks < 2; ++ks) {
;                     const bf16x8 k0 = *(const LAS bf16x8*)(ks_ + (32 * jp + fr) * 72 + 32 * ks + 8 * fq);
;                     const bf16x8 k1 = *(const LAS bf16x8*)(ks_ + (32 * jp + 16 + fr) * 72 + 32 * ks + 8 * fq);
;                     c0 = __builtin_amdgcn_mfma_f32_16x16x32_bf16(k0, qf[ks], c0, 0, 0, 0);
;                     c1 = __builtin_amdgcn_mfma_f32_16x16x32_bf16(k1, qf[ks], c1, 0, 0, 0);
;                 }
;                 float v[8];
; #pragma unroll
;                 for (int r = 0; r < 4; ++r) {
;                     const int j0 = 32 * jp + 4 * fq + r, j1 = j0 + 16;
;                     const int d0 = i_loc - j0, d1 = i_loc - j1;
;                     v[r] = c0[r] * (d0 >= 0 ? exp2f((float)d0 * l2f) : exp2f((float)(-d0) * l2b));
;                     v[4 + r] = c1[r] * (d1 >= 0 ? exp2f((float)d1 * l2f) : exp2f((float)(-d1) * l2b));
;                 }
;                 u32x4 pv; pv[0] = pk2(v[0], v[1]); pv[1] = pk2(v[2], v[3]); pv[2] = pk2(v[4], v[5]); pv[3] = pk2(v[6], v[7]);
;                 pa[jp] = __builtin_bit_cast(bf16x8, pv);
;             }
	v_mfma_f32_16x16x32_bf16 v[54:57], v[62:65], v[42:45], v[54:57]
	v_mul_f32_e32 v62, v66, v162
	v_mul_f32_e32 v63, v67, v161
	v_cndmask_b32_e64 v62, v62, v63, s[4:5]
	v_cmp_gt_f32_e64 s[74:75], s3, v62
	v_readlane_b32 s4, v254, 54
	v_mul_f32_e32 v64, v67, v163
	v_cndmask_b32_e64 v63, 0, v183, s[74:75]
	v_add_f32_e32 v62, v62, v63
	v_exp_f32_e32 v62, v62
	v_cndmask_b32_e64 v63, 0, v184, s[74:75]
	v_readlane_b32 s5, v254, 55
	v_mul_f32_e32 v65, v67, v165
	v_ldexp_f32 v62, v62, v63
	v_mul_f32_e32 v63, v66, v164
	v_cndmask_b32_e64 v63, v63, v64, s[4:5]
	v_cmp_gt_f32_e64 s[74:75], s3, v63
	v_readlane_b32 s4, v254, 56
	v_readlane_b32 s5, v254, 57
	v_cndmask_b32_e64 v64, 0, v183, s[74:75]
	v_add_f32_e32 v63, v63, v64
	v_exp_f32_e32 v63, v63
	v_cndmask_b32_e64 v64, 0, v184, s[74:75]
	v_mfma_f32_16x16x32_bf16 v[58:61], v[58:61], v[46:49], 0
	v_ldexp_f32 v64, v63, v64
	v_mul_f32_e32 v63, v66, v166
	v_cndmask_b32_e64 v63, v63, v65, s[4:5]
	v_cmp_gt_f32_e64 s[74:75], s3, v63
	v_readlane_b32 s4, v254, 58
	v_readlane_b32 s5, v254, 59
	v_cndmask_b32_e64 v65, 0, v183, s[74:75]
	v_add_f32_e32 v63, v63, v65
	v_exp_f32_e32 v63, v63
	v_cndmask_b32_e64 v65, 0, v184, s[74:75]
	s_waitcnt lgkmcnt(0)
	v_mfma_f32_16x16x32_bf16 v[58:61], v[68:71], v[42:45], v[58:61]
	v_ldexp_f32 v63, v63, v65
	v_pk_mul_f32 v[54:55], v[54:55], v[62:63]
	v_mul_f32_e32 v62, v66, v168
	v_mul_f32_e32 v63, v67, v167
	v_cndmask_b32_e64 v62, v62, v63, s[4:5]
	v_cmp_gt_f32_e64 s[74:75], s3, v62
	v_readlane_b32 s4, v254, 60
	v_readlane_b32 s5, v254, 61
	v_cndmask_b32_e64 v63, 0, v183, s[74:75]
	v_add_f32_e32 v62, v62, v63
	v_exp_f32_e32 v62, v62
	v_cndmask_b32_e64 v63, 0, v184, s[74:75]
	v_cvt_pk_bf16_f32 v54, v54, v55
	v_ldexp_f32 v65, v62, v63
	v_mul_f32_e32 v62, v66, v189
	v_mul_f32_e32 v63, v67, v169
	v_cndmask_b32_e64 v62, v62, v63, s[4:5]
	v_cmp_gt_f32_e64 s[74:75], s3, v62
	v_readlane_b32 s4, v254, 62
	v_pk_mul_f32 v[58:59], v[58:59], v[64:65]
	v_cndmask_b32_e64 v63, 0, v183, s[74:75]
	v_add_f32_e32 v62, v62, v63
	v_exp_f32_e32 v62, v62
	v_cndmask_b32_e64 v63, 0, v184, s[74:75]
	v_mul_f32_e32 v64, v67, v190
	v_readlane_b32 s5, v254, 63
	v_ldexp_f32 v62, v62, v63
	v_mul_f32_e32 v63, v66, v191
	v_cndmask_b32_e64 v63, v63, v64, s[4:5]
	v_cmp_gt_f32_e64 s[74:75], s3, v63
	v_readlane_b32 s4, v255, 0
	v_mul_f32_e32 v65, v67, v192
	v_cndmask_b32_e64 v64, 0, v183, s[74:75]
	v_add_f32_e32 v63, v63, v64
	v_exp_f32_e32 v63, v63
	v_cndmask_b32_e64 v64, 0, v184, s[74:75]
	v_readlane_b32 s5, v255, 1
	v_ldexp_f32 v64, v63, v64
	v_mul_f32_e32 v63, v66, v193
	v_cndmask_b32_e64 v63, v63, v65, s[4:5]
	v_cmp_gt_f32_e64 s[74:75], s3, v63
	v_readlane_b32 s4, v255, 2
	v_readlane_b32 s5, v255, 3
	v_cndmask_b32_e64 v65, 0, v183, s[74:75]
	v_add_f32_e32 v63, v63, v65
	v_exp_f32_e32 v63, v63
	v_cndmask_b32_e64 v65, 0, v184, s[74:75]
	v_ldexp_f32 v63, v63, v65
	v_pk_mul_f32 v[56:57], v[56:57], v[62:63]
	v_mul_f32_e32 v62, v66, v195
	v_mul_f32_e32 v63, v67, v194
	v_cndmask_b32_e64 v62, v62, v63, s[4:5]
	v_cmp_gt_f32_e64 s[74:75], s3, v62
	v_cvt_pk_bf16_f32 v55, v56, v57
	v_cvt_pk_bf16_f32 v56, v58, v59
	v_cndmask_b32_e64 v63, 0, v183, s[74:75]
	v_add_f32_e32 v62, v62, v63
	v_exp_f32_e32 v62, v62
	v_cndmask_b32_e64 v63, 0, v184, s[74:75]
	v_readlane_b32 s4, v255, 4
	v_readlane_b32 s5, v255, 5
	v_ldexp_f32 v65, v62, v63
	v_pk_mul_f32 v[60:61], v[60:61], v[64:65]
	s_nop 0
	v_cvt_pk_bf16_f32 v57, v60, v61
	ds_read_b128 v[58:61], v196
	ds_read_b128 v[62:65], v196 offset:2304
	s_waitcnt lgkmcnt(1)
	v_mfma_f32_16x16x32_bf16 v[58:61], v[58:61], v[46:49], 0
	ds_read_b128 v[68:71], v196 offset:64
	ds_read_b128 v[72:75], v196 offset:2368
	s_waitcnt lgkmcnt(1)
	v_mfma_f32_16x16x32_bf16 v[58:61], v[68:71], v[42:45], v[58:61]
	v_mul_f32_e32 v68, v66, v198
	v_mul_f32_e32 v69, v67, v197
	v_cndmask_b32_e64 v68, v68, v69, s[4:5]
	v_cmp_gt_f32_e64 s[74:75], s3, v68
	v_readlane_b32 s4, v255, 6
	v_mul_f32_e32 v70, v67, v199
	v_cndmask_b32_e64 v69, 0, v183, s[74:75]
	v_add_f32_e32 v68, v68, v69
	v_exp_f32_e32 v68, v68
	v_cndmask_b32_e64 v69, 0, v184, s[74:75]
	v_readlane_b32 s5, v255, 7
	v_mul_f32_e32 v71, v67, v201
	v_ldexp_f32 v68, v68, v69
	v_mul_f32_e32 v69, v66, v200
	v_cndmask_b32_e64 v69, v69, v70, s[4:5]
	v_cmp_gt_f32_e64 s[74:75], s3, v69
	v_readlane_b32 s4, v255, 8
	v_readlane_b32 s5, v255, 9
	v_cndmask_b32_e64 v70, 0, v183, s[74:75]
	v_add_f32_e32 v69, v69, v70
	v_exp_f32_e32 v69, v69
	v_cndmask_b32_e64 v70, 0, v184, s[74:75]
	v_mfma_f32_16x16x32_bf16 v[62:65], v[62:65], v[46:49], 0
	v_ldexp_f32 v70, v69, v70
	v_mul_f32_e32 v69, v66, v202
	v_cndmask_b32_e64 v69, v69, v71, s[4:5]
	v_cmp_gt_f32_e64 s[74:75], s3, v69
	v_readlane_b32 s4, v255, 10
	v_readlane_b32 s5, v255, 11
	v_cndmask_b32_e64 v71, 0, v183, s[74:75]
	v_add_f32_e32 v69, v69, v71
	v_exp_f32_e32 v69, v69
	v_cndmask_b32_e64 v71, 0, v184, s[74:75]
	s_waitcnt lgkmcnt(0)
; #define LAS __attribute__((address_space(3)))
; __device__ __forceinline__ unsigned pk2(float lo, float hi) { const f32x2_t v = {lo, hi}; const bf16v2_t b = __builtin_convertvector(v, bf16v2_t); return __builtin_bit_cast(unsigned, b); }
; __device__ __forceinline__ void ret_out_phase(const Args& A, Frame& F, int l, bool lastl, bf16_t* ARET, bf16_t* ALRU) {
;     ...
;         bf16x8 pa[4];
;         {
;             const int i_loc = 16 * w + fr;
; #pragma unroll
;             for (int jp = 0; jp < 4; ++jp) {
;                 f32x4 c0 = (f32x4){0.f, 0.f, 0.f, 0.f}, c1 = c0;
; #pragma unroll
;                 for (int ks = 0; ks < 2; ++ks) {
;                     const bf16x8 k0 = *(const LAS bf16x8*)(ks_ + (32 * jp + fr) * 72 + 32 * ks + 8 * fq);
;                     const bf16x8 k1 = *(const LAS bf16x8*)(ks_ + (32 * jp + 16 + fr) * 72 + 32 * ks + 8 * fq);
;                     c0 = __builtin_amdgcn_mfma_f32_16x16x32_bf16(k0, qf[ks], c0, 0, 0, 0);
;                     c1 = __builtin_amdgcn_mfma_f32_16x16x32_bf16(k1, qf[ks], c1, 0, 0, 0);
;                 }
;                 float v[8];
; #pragma unroll
;                 for (int r = 0; r < 4; ++r) {
;                     const int j0 = 32 * jp + 4 * fq + r, j1 = j0 + 16;
;                     const int d0 = i_loc - j0, d1 = i_loc - j1;
;                     v[r] = c0[r] * (d0 >= 0 ? exp2f((float)d0 * l2f) : exp2f((float)(-d0) * l2b));
;                     v[4 + r] = c1[r] * (d1 >= 0 ? exp2f((float)d1 * l2f) : exp2f((float)(-d1) * l2b));
;                 }
;                 u32x4 pv; pv[0] = pk2(v[0], v[1]); pv[1] = pk2(v[2], v[3]); pv[2] = pk2(v[4], v[5]); pv[3] = pk2(v[6], v[7]);
;                 pa[jp] = __builtin_bit_cast(bf16x8, pv);
;             }
	v_mfma_f32_16x16x32_bf16 v[62:65], v[72:75], v[42:45], v[62:65]
	v_ldexp_f32 v69, v69, v71
	v_pk_mul_f32 v[58:59], v[58:59], v[68:69]
	v_mul_f32_e32 v68, v66, v204
	v_mul_f32_e32 v69, v67, v203
	v_cndmask_b32_e64 v68, v68, v69, s[4:5]
	v_cmp_gt_f32_e64 s[74:75], s3, v68
	v_readlane_b32 s4, v255, 12
	v_readlane_b32 s5, v255, 13
	v_cndmask_b32_e64 v69, 0, v183, s[74:75]
	v_add_f32_e32 v68, v68, v69
	v_exp_f32_e32 v68, v68
	v_cndmask_b32_e64 v69, 0, v184, s[74:75]
	v_cvt_pk_bf16_f32 v58, v58, v59
	v_ldexp_f32 v71, v68, v69
	v_mul_f32_e32 v68, v66, v206
	v_mul_f32_e32 v69, v67, v205
	v_cndmask_b32_e64 v68, v68, v69, s[4:5]
	v_cmp_gt_f32_e64 s[74:75], s3, v68
	v_readlane_b32 s4, v255, 14
	v_pk_mul_f32 v[62:63], v[62:63], v[70:71]
	v_cndmask_b32_e64 v69, 0, v183, s[74:75]
	v_add_f32_e32 v68, v68, v69
	v_exp_f32_e32 v68, v68
	v_cndmask_b32_e64 v69, 0, v184, s[74:75]
	v_mul_f32_e32 v70, v67, v207
	v_readlane_b32 s5, v255, 15
	v_ldexp_f32 v68, v68, v69
	v_mul_f32_e32 v69, v66, v208
	v_cndmask_b32_e64 v69, v69, v70, s[4:5]
	v_cmp_gt_f32_e64 s[74:75], s3, v69
	v_readlane_b32 s4, v255, 16
	v_mul_f32_e32 v71, v67, v209
	v_cndmask_b32_e64 v70, 0, v183, s[74:75]
	v_add_f32_e32 v69, v69, v70
	v_exp_f32_e32 v69, v69
	v_cndmask_b32_e64 v70, 0, v184, s[74:75]
	v_readlane_b32 s5, v255, 17
	v_ldexp_f32 v70, v69, v70
	v_mul_f32_e32 v69, v66, v210
	v_cndmask_b32_e64 v69, v69, v71, s[4:5]
	v_cmp_gt_f32_e64 s[74:75], s3, v69
	v_readlane_b32 s4, v255, 18
	v_readlane_b32 s5, v255, 19
	v_cndmask_b32_e64 v71, 0, v183, s[74:75]
	v_add_f32_e32 v69, v69, v71
	v_exp_f32_e32 v69, v69
	v_cndmask_b32_e64 v71, 0, v184, s[74:75]
	v_ldexp_f32 v69, v69, v71
	v_pk_mul_f32 v[60:61], v[60:61], v[68:69]
	v_mul_f32_e32 v68, v66, v212
	v_mul_f32_e32 v69, v67, v211
	v_cndmask_b32_e64 v68, v68, v69, s[4:5]
	v_cmp_gt_f32_e64 s[74:75], s3, v68
	v_cvt_pk_bf16_f32 v59, v60, v61
	v_cvt_pk_bf16_f32 v60, v62, v63
	v_cndmask_b32_e64 v69, 0, v183, s[74:75]
	v_add_f32_e32 v68, v68, v69
	v_exp_f32_e32 v68, v68
	v_cndmask_b32_e64 v69, 0, v184, s[74:75]
	v_readlane_b32 s4, v255, 20
	v_readlane_b32 s5, v255, 21
	v_ldexp_f32 v71, v68, v69
	v_pk_mul_f32 v[64:65], v[64:65], v[70:71]
	s_nop 0
	v_cvt_pk_bf16_f32 v61, v64, v65
	ds_read_b128 v[62:65], v213
	ds_read_b128 v[68:71], v213 offset:2304
	s_waitcnt lgkmcnt(1)
	v_mfma_f32_16x16x32_bf16 v[62:65], v[62:65], v[46:49], 0
	ds_read_b128 v[72:75], v213 offset:64
	ds_read_b128 v[76:79], v213 offset:2368
	s_waitcnt lgkmcnt(1)
	v_mfma_f32_16x16x32_bf16 v[62:65], v[72:75], v[42:45], v[62:65]
	v_mul_f32_e32 v72, v66, v215
	v_mul_f32_e32 v73, v67, v214
	v_cndmask_b32_e64 v72, v72, v73, s[4:5]
	v_cmp_gt_f32_e64 s[74:75], s3, v72
	v_readlane_b32 s4, v255, 22
	v_mul_f32_e32 v74, v67, v216
	v_cndmask_b32_e64 v73, 0, v183, s[74:75]
	v_add_f32_e32 v72, v72, v73
	v_exp_f32_e32 v72, v72
	v_cndmask_b32_e64 v73, 0, v184, s[74:75]
	v_readlane_b32 s5, v255, 23
	v_mul_f32_e32 v75, v67, v218
	v_ldexp_f32 v72, v72, v73
	v_mul_f32_e32 v73, v66, v217
	v_cndmask_b32_e64 v73, v73, v74, s[4:5]
	v_cmp_gt_f32_e64 s[74:75], s3, v73
	v_readlane_b32 s4, v255, 24
	v_readlane_b32 s5, v255, 25
	v_cndmask_b32_e64 v74, 0, v183, s[74:75]
	v_add_f32_e32 v73, v73, v74
	v_exp_f32_e32 v73, v73
	v_cndmask_b32_e64 v74, 0, v184, s[74:75]
	v_mfma_f32_16x16x32_bf16 v[68:71], v[68:71], v[46:49], 0
	v_ldexp_f32 v74, v73, v74
	v_mul_f32_e32 v73, v66, v219
	v_cndmask_b32_e64 v73, v73, v75, s[4:5]
	v_cmp_gt_f32_e64 s[74:75], s3, v73
	v_readlane_b32 s4, v255, 26
	v_readlane_b32 s5, v255, 27
	v_cndmask_b32_e64 v75, 0, v183, s[74:75]
	v_add_f32_e32 v73, v73, v75
	v_exp_f32_e32 v73, v73
	v_cndmask_b32_e64 v75, 0, v184, s[74:75]
	s_waitcnt lgkmcnt(0)
	v_mfma_f32_16x16x32_bf16 v[68:71], v[76:79], v[42:45], v[68:71]
	v_ldexp_f32 v73, v73, v75
	v_pk_mul_f32 v[62:63], v[62:63], v[72:73]
	v_mul_f32_e32 v72, v66, v221
	v_mul_f32_e32 v73, v67, v220
	v_cndmask_b32_e64 v72, v72, v73, s[4:5]
	v_cmp_gt_f32_e64 s[74:75], s3, v72
	v_readlane_b32 s4, v255, 28
	v_readlane_b32 s5, v255, 29
	v_cndmask_b32_e64 v73, 0, v183, s[74:75]
	v_add_f32_e32 v72, v72, v73
	v_exp_f32_e32 v72, v72
	v_cndmask_b32_e64 v73, 0, v184, s[74:75]
	v_cvt_pk_bf16_f32 v62, v62, v63
	v_ldexp_f32 v75, v72, v73
	v_mul_f32_e32 v72, v66, v223
	v_mul_f32_e32 v73, v67, v222
	v_cndmask_b32_e64 v72, v72, v73, s[4:5]
	v_cmp_gt_f32_e64 s[74:75], s3, v72
	v_pk_mul_f32 v[68:69], v[68:69], v[74:75]
	v_mul_f32_e32 v74, v67, v224
	v_cndmask_b32_e64 v73, 0, v183, s[74:75]
	v_add_f32_e32 v72, v72, v73
	v_exp_f32_e32 v72, v72
	v_cndmask_b32_e64 v73, 0, v184, s[74:75]
	v_mul_f32_e32 v75, v67, v226
	v_ldexp_f32 v72, v72, v73
	v_mul_f32_e32 v73, v66, v225
	v_cndmask_b32_e64 v73, v73, v74, s[66:67]
	v_cmp_gt_f32_e64 s[74:75], s3, v73
	s_nop 1
	v_cndmask_b32_e64 v74, 0, v183, s[74:75]
	v_add_f32_e32 v73, v73, v74
	v_exp_f32_e32 v73, v73
	v_cndmask_b32_e64 v74, 0, v184, s[74:75]
	v_ldexp_f32 v74, v73, v74
	v_mul_f32_e32 v73, v66, v227
	v_cndmask_b32_e64 v73, v73, v75, s[68:69]
	v_cmp_gt_f32_e64 s[74:75], s3, v73
	s_nop 1
	v_cndmask_b32_e64 v75, 0, v183, s[74:75]
	v_add_f32_e32 v73, v73, v75
	v_exp_f32_e32 v73, v73
	v_cndmask_b32_e64 v75, 0, v184, s[74:75]
	v_ldexp_f32 v73, v73, v75
	v_pk_mul_f32 v[64:65], v[64:65], v[72:73]
	v_mul_f32_e32 v72, v66, v229
	v_mul_f32_e32 v73, v67, v228
	v_cndmask_b32_e64 v72, v72, v73, s[70:71]
	v_cmp_gt_f32_e64 s[74:75], s3, v72
	v_cvt_pk_bf16_f32 v63, v64, v65
	v_cvt_pk_bf16_f32 v64, v68, v69
	v_cndmask_b32_e64 v73, 0, v183, s[74:75]
	v_mul_f32_e32 v68, v66, v103
	v_add_f32_e32 v72, v72, v73
	v_cndmask_b32_e64 v73, 0, v184, s[74:75]
	v_cmp_gt_f32_e64 s[74:75], s3, v68
	v_exp_f32_e32 v72, v72
	v_and_b32_e32 v69, 0xffff0000, v46
; #define LAS __attribute__((address_space(3)))
; __device__ __forceinline__ unsigned pk2(float lo, float hi) { const f32x2_t v = {lo, hi}; const bf16v2_t b = __builtin_convertvector(v, bf16v2_t); return __builtin_bit_cast(unsigned, b); }
; __device__ __forceinline__ void ret_out_phase(const Args& A, Frame& F, int l, bool lastl, bf16_t* ARET, bf16_t* ALRU) {
;     ...
;                     v[r] = c0[r] * (d0 >= 0 ? exp2f((float)d0 * l2f) : exp2f((float)(-d0) * l2b));
;                     v[4 + r] = c1[r] * (d1 >= 0 ? exp2f((float)d1 * l2f) : exp2f((float)(-d1) * l2b));
;                 }
;                 u32x4 pv; pv[0] = pk2(v[0], v[1]); pv[1] = pk2(v[2], v[3]); pv[2] = pk2(v[4], v[5]); pv[3] = pk2(v[6], v[7]);
;                 pa[jp] = __builtin_bit_cast(bf16x8, pv);
;             }
;         }
;         bf16x8 qF[2], qB[2];
;         {
;             const int il = 16 * w + fr;
;             const float sF = exp2f((float)(il + 1) * l2f), sB = exp2f((float)(128 - il) * l2b);
; #pragma unroll
;             for (int ks = 0; ks < 2; ++ks) { qF[ks] = scale1(qf[ks], sF); qB[ks] = scale1(qf[ks], sB); }
;         }
;         f32x4 O[8];
; #pragma unroll
;         for (int dvt = 0; dvt < 8; ++dvt) {
;             f32x4 o = (f32x4){0.f, 0.f, 0.f, 0.f};
; #pragma unroll
;             for (int jp = 0; jp < 4; ++jp) {
;                 const u32x2 lo = *(const LAS u32x2*)(vts + (16 * dvt + fr) * 136 + 32 * jp + 4 * fq);
;                 const u32x2 hi = *(const LAS u32x2*)(vts + (16 * dvt + fr) * 136 + 32 * jp + 16 + 4 * fq);
;                 u32x4 bv; bv[0] = lo.x; bv[1] = lo.y; bv[2] = hi.x; bv[3] = hi.y;
;                 o = __builtin_amdgcn_mfma_f32_16x16x32_bf16(pa[jp], __builtin_bit_cast(bf16x8, bv), o, 0, 0, 0);
;             }
; #pragma unroll
;             for (int ks = 0; ks < 2; ++ks) {
;                 const bf16x8 sf = *(const LAS bf16x8*)(sfs + (16 * dvt + fr) * 72 + 32 * ks + 8 * fq);
;                 const bf16x8 sb = *(const LAS bf16x8*)(sbs + (16 * dvt + fr) * 72 + 32 * ks + 8 * fq);
;                 o = __builtin_amdgcn_mfma_f32_16x16x32_bf16(qF[ks], sf, o, 0, 0, 0);
;                 o = __builtin_amdgcn_mfma_f32_16x16x32_bf16(qB[ks], sb, o, 0, 0, 0);
;             }
;             O[dvt] = o;
	v_cndmask_b32_e64 v68, 0, v183, s[74:75]
	v_fmac_f32_e32 v68, v66, v103
	v_exp_f32_e32 v66, v68
	v_ldexp_f32 v75, v72, v73
	v_cndmask_b32_e64 v68, 0, v184, s[74:75]
	v_pk_mul_f32 v[70:71], v[70:71], v[74:75]
	v_ldexp_f32 v74, v66, v68
	v_mul_f32_e32 v66, v67, v105
	v_cmp_gt_f32_e64 s[74:75], s3, v66
	v_lshlrev_b32_e32 v68, 16, v46
	v_cvt_pk_bf16_f32 v65, v70, v71
	v_cndmask_b32_e64 v66, 0, v183, s[74:75]
	v_fmac_f32_e32 v66, v67, v105
	v_exp_f32_e32 v66, v66
	v_cndmask_b32_e64 v67, 0, v184, s[74:75]
	v_ldexp_f32 v76, v66, v67
	v_pk_mul_f32 v[66:67], v[74:75], v[68:69] op_sel_hi:[0,1]
	v_pk_mul_f32 v[68:69], v[76:77], v[68:69] op_sel_hi:[0,1]
	v_cvt_pk_bf16_f32 v46, v68, v69
	v_lshlrev_b32_e32 v68, 16, v47
	v_and_b32_e32 v69, 0xffff0000, v47
	v_pk_mul_f32 v[70:71], v[74:75], v[68:69] op_sel_hi:[0,1]
	v_cvt_pk_bf16_f32 v66, v66, v67
	v_cvt_pk_bf16_f32 v67, v70, v71
	v_pk_mul_f32 v[68:69], v[76:77], v[68:69] op_sel_hi:[0,1]
	v_lshlrev_b32_e32 v70, 16, v48
	v_and_b32_e32 v71, 0xffff0000, v48
	v_cvt_pk_bf16_f32 v47, v68, v69
	v_pk_mul_f32 v[68:69], v[74:75], v[70:71] op_sel_hi:[0,1]
	v_pk_mul_f32 v[70:71], v[76:77], v[70:71] op_sel_hi:[0,1]
	v_cvt_pk_bf16_f32 v48, v70, v71
	v_lshlrev_b32_e32 v70, 16, v49
	v_and_b32_e32 v71, 0xffff0000, v49
	v_pk_mul_f32 v[72:73], v[74:75], v[70:71] op_sel_hi:[0,1]
	v_cvt_pk_bf16_f32 v68, v68, v69
	v_cvt_pk_bf16_f32 v69, v72, v73
	v_pk_mul_f32 v[70:71], v[76:77], v[70:71] op_sel_hi:[0,1]
	v_lshlrev_b32_e32 v72, 16, v42
	v_and_b32_e32 v73, 0xffff0000, v42
	v_cvt_pk_bf16_f32 v49, v70, v71
	v_pk_mul_f32 v[70:71], v[74:75], v[72:73] op_sel_hi:[0,1]
	v_pk_mul_f32 v[72:73], v[76:77], v[72:73] op_sel_hi:[0,1]
	v_cvt_pk_bf16_f32 v42, v72, v73
	v_lshlrev_b32_e32 v72, 16, v43
	v_and_b32_e32 v73, 0xffff0000, v43
	v_pk_mul_f32 v[78:79], v[74:75], v[72:73] op_sel_hi:[0,1]
	v_cvt_pk_bf16_f32 v70, v70, v71
	v_cvt_pk_bf16_f32 v71, v78, v79
	v_pk_mul_f32 v[72:73], v[76:77], v[72:73] op_sel_hi:[0,1]
	v_lshlrev_b32_e32 v78, 16, v44
	v_and_b32_e32 v79, 0xffff0000, v44
	v_cvt_pk_bf16_f32 v43, v72, v73
	v_pk_mul_f32 v[72:73], v[74:75], v[78:79] op_sel_hi:[0,1]
	v_pk_mul_f32 v[78:79], v[76:77], v[78:79] op_sel_hi:[0,1]
	v_cvt_pk_bf16_f32 v44, v78, v79
	v_lshlrev_b32_e32 v78, 16, v45
	v_and_b32_e32 v79, 0xffff0000, v45
	v_pk_mul_f32 v[74:75], v[74:75], v[78:79] op_sel_hi:[0,1]
	v_cvt_pk_bf16_f32 v72, v72, v73
	v_cvt_pk_bf16_f32 v73, v74, v75
	v_pk_mul_f32 v[74:75], v[76:77], v[78:79] op_sel_hi:[0,1]
	v_cvt_pk_bf16_f32 v45, v74, v75
	ds_read2_b64 v[74:77], v82 offset1:4
	ds_read2_b64 v[78:81], v82 offset0:8 offset1:12
	s_waitcnt lgkmcnt(1)
	v_mfma_f32_16x16x32_bf16 v[74:77], v[50:53], v[74:77], 0
	s_waitcnt lgkmcnt(0)
	v_mfma_f32_16x16x32_bf16 v[74:77], v[54:57], v[78:81], v[74:77]
	ds_read2_b64 v[78:81], v82 offset0:16 offset1:20
	s_waitcnt lgkmcnt(0)
	v_mfma_f32_16x16x32_bf16 v[74:77], v[58:61], v[78:81], v[74:77]
	ds_read2_b64 v[78:81], v82 offset0:24 offset1:28
	s_waitcnt lgkmcnt(0)
	v_mfma_f32_16x16x32_bf16 v[74:77], v[62:65], v[78:81], v[74:77]
	ds_read_b128 v[78:81], v231 offset:53248
	ds_read_b128 v[82:85], v232
	s_waitcnt lgkmcnt(1)
	v_mfma_f32_16x16x32_bf16 v[74:77], v[66:69], v[78:81], v[74:77]
	s_waitcnt lgkmcnt(0)
	v_mfma_f32_16x16x32_bf16 v[74:77], v[46:49], v[82:85], v[74:77]
	ds_read_b128 v[78:81], v231 offset:53312
	ds_read_b128 v[82:85], v232 offset:64
	s_waitcnt lgkmcnt(1)
	v_mfma_f32_16x16x32_bf16 v[74:77], v[70:73], v[78:81], v[74:77]
	s_waitcnt lgkmcnt(0)
	v_mfma_f32_16x16x32_bf16 v[74:77], v[42:45], v[82:85], v[74:77]
	v_add_u32_e32 v78, 0x1100, v230
	v_add_u32_e32 v86, 0x4800, v78
	ds_read2_b64 v[78:81], v86 offset1:4
	ds_read2_b64 v[82:85], v86 offset0:8 offset1:12
	s_waitcnt lgkmcnt(1)
	v_mfma_f32_16x16x32_bf16 v[78:81], v[50:53], v[78:81], 0
	s_waitcnt lgkmcnt(0)
	v_mfma_f32_16x16x32_bf16 v[78:81], v[54:57], v[82:85], v[78:81]
	ds_read2_b64 v[82:85], v86 offset0:16 offset1:20
	s_waitcnt lgkmcnt(0)
	v_mfma_f32_16x16x32_bf16 v[78:81], v[58:61], v[82:85], v[78:81]
	ds_read2_b64 v[82:85], v86 offset0:24 offset1:28
	s_waitcnt lgkmcnt(0)
	v_mfma_f32_16x16x32_bf16 v[78:81], v[62:65], v[82:85], v[78:81]
	ds_read_b128 v[82:85], v231 offset:55552
	s_waitcnt lgkmcnt(0)
	v_mfma_f32_16x16x32_bf16 v[78:81], v[66:69], v[82:85], v[78:81]
	ds_read_b128 v[82:85], v233
	s_waitcnt lgkmcnt(0)
	v_mfma_f32_16x16x32_bf16 v[78:81], v[46:49], v[82:85], v[78:81]
	ds_read_b128 v[82:85], v231 offset:55616
	s_waitcnt lgkmcnt(0)
	v_mfma_f32_16x16x32_bf16 v[78:81], v[70:73], v[82:85], v[78:81]
	ds_read_b128 v[82:85], v233 offset:64
	s_waitcnt lgkmcnt(0)
	v_mfma_f32_16x16x32_bf16 v[78:81], v[42:45], v[82:85], v[78:81]
	v_add_u32_e32 v82, 0x2200, v230
	v_add_u32_e32 v90, 0x4800, v82
	ds_read2_b64 v[82:85], v90 offset1:4
	ds_read2_b64 v[86:89], v90 offset0:8 offset1:12
	s_waitcnt lgkmcnt(1)
	v_mfma_f32_16x16x32_bf16 v[82:85], v[50:53], v[82:85], 0
	s_waitcnt lgkmcnt(0)
	v_mfma_f32_16x16x32_bf16 v[82:85], v[54:57], v[86:89], v[82:85]
	ds_read2_b64 v[86:89], v90 offset0:16 offset1:20
	s_waitcnt lgkmcnt(0)
	v_mfma_f32_16x16x32_bf16 v[82:85], v[58:61], v[86:89], v[82:85]
	ds_read2_b64 v[86:89], v90 offset0:24 offset1:28
	s_waitcnt lgkmcnt(0)
	v_mfma_f32_16x16x32_bf16 v[82:85], v[62:65], v[86:89], v[82:85]
	ds_read_b128 v[86:89], v231 offset:57856
	s_waitcnt lgkmcnt(0)
	v_mfma_f32_16x16x32_bf16 v[82:85], v[66:69], v[86:89], v[82:85]
	ds_read_b128 v[86:89], v234
	s_waitcnt lgkmcnt(0)
	v_mfma_f32_16x16x32_bf16 v[82:85], v[46:49], v[86:89], v[82:85]
	ds_read_b128 v[86:89], v231 offset:57920
	s_waitcnt lgkmcnt(0)
	v_mfma_f32_16x16x32_bf16 v[82:85], v[70:73], v[86:89], v[82:85]
	ds_read_b128 v[86:89], v234 offset:64
	s_waitcnt lgkmcnt(0)
; #define LAS __attribute__((address_space(3)))
; __device__ __forceinline__ void ret_out_phase(const Args& A, Frame& F, int l, bool lastl, bf16_t* ARET, bf16_t* ALRU) {
;     ...
;         f32x4 O[8];
; #pragma unroll
;         for (int dvt = 0; dvt < 8; ++dvt) {
;             f32x4 o = (f32x4){0.f, 0.f, 0.f, 0.f};
; #pragma unroll
;             for (int jp = 0; jp < 4; ++jp) {
;                 const u32x2 lo = *(const LAS u32x2*)(vts + (16 * dvt + fr) * 136 + 32 * jp + 4 * fq);
;                 const u32x2 hi = *(const LAS u32x2*)(vts + (16 * dvt + fr) * 136 + 32 * jp + 16 + 4 * fq);
;                 u32x4 bv; bv[0] = lo.x; bv[1] = lo.y; bv[2] = hi.x; bv[3] = hi.y;
;                 o = __builtin_amdgcn_mfma_f32_16x16x32_bf16(pa[jp], __builtin_bit_cast(bf16x8, bv), o, 0, 0, 0);
;             }
; #pragma unroll
;             for (int ks = 0; ks < 2; ++ks) {
;                 const bf16x8 sf = *(const LAS bf16x8*)(sfs + (16 * dvt + fr) * 72 + 32 * ks + 8 * fq);
;                 const bf16x8 sb = *(const LAS bf16x8*)(sbs + (16 * dvt + fr) * 72 + 32 * ks + 8 * fq);
;                 o = __builtin_amdgcn_mfma_f32_16x16x32_bf16(qF[ks], sf, o, 0, 0, 0);
;                 o = __builtin_amdgcn_mfma_f32_16x16x32_bf16(qB[ks], sb, o, 0, 0, 0);
;             }
;             O[dvt] = o;
;             __builtin_amdgcn_sched_barrier(0);
;         }
	v_mfma_f32_16x16x32_bf16 v[82:85], v[42:45], v[86:89], v[82:85]
	v_add_u32_e32 v86, 0x3300, v230
	v_add_u32_e32 v94, 0x4800, v86
	ds_read2_b64 v[86:89], v94 offset1:4
	ds_read2_b64 v[90:93], v94 offset0:8 offset1:12
	s_waitcnt lgkmcnt(1)
	v_mfma_f32_16x16x32_bf16 v[86:89], v[50:53], v[86:89], 0
	s_waitcnt lgkmcnt(0)
	v_mfma_f32_16x16x32_bf16 v[86:89], v[54:57], v[90:93], v[86:89]
	ds_read2_b64 v[90:93], v94 offset0:16 offset1:20
	s_waitcnt lgkmcnt(0)
	v_mfma_f32_16x16x32_bf16 v[86:89], v[58:61], v[90:93], v[86:89]
	ds_read2_b64 v[90:93], v94 offset0:24 offset1:28
	s_waitcnt lgkmcnt(0)
	v_mfma_f32_16x16x32_bf16 v[86:89], v[62:65], v[90:93], v[86:89]
	ds_read_b128 v[90:93], v160 offset:55552
	s_waitcnt lgkmcnt(0)
	v_mfma_f32_16x16x32_bf16 v[86:89], v[66:69], v[90:93], v[86:89]
	ds_read_b128 v[90:93], v235
	s_waitcnt lgkmcnt(0)
	v_mfma_f32_16x16x32_bf16 v[86:89], v[46:49], v[90:93], v[86:89]
	ds_read_b128 v[90:93], v160 offset:55616
	s_waitcnt lgkmcnt(0)
	v_mfma_f32_16x16x32_bf16 v[86:89], v[70:73], v[90:93], v[86:89]
	ds_read_b128 v[90:93], v235 offset:64
	s_waitcnt lgkmcnt(0)
	v_mfma_f32_16x16x32_bf16 v[86:89], v[42:45], v[90:93], v[86:89]
	v_add_u32_e32 v90, 0x4400, v230
	v_add_u32_e32 v98, 0x4800, v90
	ds_read2_b64 v[90:93], v98 offset1:4
	ds_read2_b64 v[94:97], v98 offset0:8 offset1:12
	s_waitcnt lgkmcnt(1)
	v_mfma_f32_16x16x32_bf16 v[90:93], v[50:53], v[90:93], 0
	s_waitcnt lgkmcnt(0)
	v_mfma_f32_16x16x32_bf16 v[90:93], v[54:57], v[94:97], v[90:93]
	ds_read2_b64 v[94:97], v98 offset0:16 offset1:20
	s_waitcnt lgkmcnt(0)
	v_mfma_f32_16x16x32_bf16 v[90:93], v[58:61], v[94:97], v[90:93]
	ds_read2_b64 v[94:97], v98 offset0:24 offset1:28
	s_waitcnt lgkmcnt(0)
	v_mfma_f32_16x16x32_bf16 v[90:93], v[62:65], v[94:97], v[90:93]
	ds_read_b128 v[94:97], v236 offset:53248
	s_waitcnt lgkmcnt(0)
	v_mfma_f32_16x16x32_bf16 v[90:93], v[66:69], v[94:97], v[90:93]
	ds_read_b128 v[94:97], v237
	s_waitcnt lgkmcnt(0)
	v_mfma_f32_16x16x32_bf16 v[90:93], v[46:49], v[94:97], v[90:93]
	ds_read_b128 v[94:97], v236 offset:53312
	s_waitcnt lgkmcnt(0)
	v_mfma_f32_16x16x32_bf16 v[90:93], v[70:73], v[94:97], v[90:93]
	ds_read_b128 v[94:97], v237 offset:64
	s_waitcnt lgkmcnt(0)
	v_mfma_f32_16x16x32_bf16 v[90:93], v[42:45], v[94:97], v[90:93]
	v_add_u32_e32 v94, 0x5500, v230
	v_add_u32_e32 v129, 0x4800, v94
	ds_read2_b64 v[94:97], v129 offset1:4
	ds_read2_b64 v[98:101], v129 offset0:8 offset1:12
	s_waitcnt lgkmcnt(1)
	v_mfma_f32_16x16x32_bf16 v[94:97], v[50:53], v[94:97], 0
	s_waitcnt lgkmcnt(0)
	v_mfma_f32_16x16x32_bf16 v[94:97], v[54:57], v[98:101], v[94:97]
	ds_read2_b64 v[98:101], v129 offset0:16 offset1:20
	s_waitcnt lgkmcnt(0)
	v_mfma_f32_16x16x32_bf16 v[94:97], v[58:61], v[98:101], v[94:97]
	ds_read2_b64 v[98:101], v129 offset0:24 offset1:28
	s_waitcnt lgkmcnt(0)
	v_mfma_f32_16x16x32_bf16 v[94:97], v[62:65], v[98:101], v[94:97]
	ds_read_b128 v[98:101], v238 offset:53248
	s_waitcnt lgkmcnt(0)
	v_mfma_f32_16x16x32_bf16 v[94:97], v[66:69], v[98:101], v[94:97]
	ds_read_b128 v[98:101], v239
	s_waitcnt lgkmcnt(0)
	v_mfma_f32_16x16x32_bf16 v[94:97], v[46:49], v[98:101], v[94:97]
	ds_read_b128 v[98:101], v238 offset:53312
	s_waitcnt lgkmcnt(0)
	v_mfma_f32_16x16x32_bf16 v[94:97], v[70:73], v[98:101], v[94:97]
	ds_read_b128 v[98:101], v239 offset:64
	s_waitcnt lgkmcnt(0)
	v_mfma_f32_16x16x32_bf16 v[94:97], v[42:45], v[98:101], v[94:97]
	v_add_u32_e32 v98, 0x6600, v230
	v_add_u32_e32 v129, 0x4800, v98
	ds_read2_b64 v[98:101], v129 offset1:4
	ds_read2_b64 v[250:253], v129 offset0:8 offset1:12
	s_waitcnt lgkmcnt(1)
	v_mfma_f32_16x16x32_bf16 v[98:101], v[50:53], v[98:101], 0
	s_waitcnt lgkmcnt(0)
	v_mfma_f32_16x16x32_bf16 v[98:101], v[54:57], v[250:253], v[98:101]
	ds_read2_b64 v[250:253], v129 offset0:16 offset1:20
	s_waitcnt lgkmcnt(0)
	v_mfma_f32_16x16x32_bf16 v[98:101], v[58:61], v[250:253], v[98:101]
	ds_read2_b64 v[250:253], v129 offset0:24 offset1:28
	s_waitcnt lgkmcnt(0)
	v_mfma_f32_16x16x32_bf16 v[98:101], v[62:65], v[250:253], v[98:101]
	ds_read_b128 v[250:253], v240 offset:53248
	s_waitcnt lgkmcnt(0)
	v_mfma_f32_16x16x32_bf16 v[98:101], v[66:69], v[250:253], v[98:101]
	ds_read_b128 v[250:253], v241
	s_waitcnt lgkmcnt(0)
	v_mfma_f32_16x16x32_bf16 v[98:101], v[46:49], v[250:253], v[98:101]
	ds_read_b128 v[250:253], v240 offset:53312
	s_waitcnt lgkmcnt(0)
	v_mfma_f32_16x16x32_bf16 v[98:101], v[70:73], v[250:253], v[98:101]
	ds_read_b128 v[250:253], v241 offset:64
	s_waitcnt lgkmcnt(0)
	v_mfma_f32_16x16x32_bf16 v[98:101], v[42:45], v[250:253], v[98:101]
	v_add_u32_e32 v129, 0x4800, v242
	ds_read2_b64 v[250:253], v129 offset1:4
	s_waitcnt lgkmcnt(0)
	v_mfma_f32_16x16x32_bf16 v[50:53], v[50:53], v[250:253], 0
	ds_read2_b64 v[250:253], v129 offset0:8 offset1:12
	s_waitcnt lgkmcnt(0)
	v_mfma_f32_16x16x32_bf16 v[50:53], v[54:57], v[250:253], v[50:53]
	ds_read2_b64 v[54:57], v129 offset0:16 offset1:20
	s_waitcnt lgkmcnt(0)
	v_mfma_f32_16x16x32_bf16 v[50:53], v[58:61], v[54:57], v[50:53]
	ds_read2_b64 v[54:57], v129 offset0:24 offset1:28
	s_waitcnt lgkmcnt(0)
	v_mfma_f32_16x16x32_bf16 v[50:53], v[62:65], v[54:57], v[50:53]
	ds_read_b128 v[54:57], v243 offset:53248
	ds_read_b128 v[58:61], v243 offset:53312
	s_waitcnt lgkmcnt(1)
	v_mfma_f32_16x16x32_bf16 v[50:53], v[66:69], v[54:57], v[50:53]
	ds_read_b128 v[54:57], v244
	ds_read_b128 v[62:65], v244 offset:64
	s_waitcnt lgkmcnt(1)
	v_mfma_f32_16x16x32_bf16 v[46:49], v[46:49], v[54:57], v[50:53]
	v_mfma_f32_16x16x32_bf16 v[46:49], v[70:73], v[58:61], v[46:49]
	s_waitcnt lgkmcnt(0)
; #define LAS __attribute__((address_space(3)))
; __device__ __forceinline__ bf16_t f2bf(float f) { return (bf16_t)(pk2(f, 0.f) & 0xffffu); }
; __device__ __forceinline__ void ret_out_phase(const Args& A, Frame& F, int l, bool lastl, bf16_t* ARET, bf16_t* ALRU) {
;     ...
;         f32x4 O[8];
; #pragma unroll
;         for (int dvt = 0; dvt < 8; ++dvt) {
;             f32x4 o = (f32x4){0.f, 0.f, 0.f, 0.f};
; #pragma unroll
;             for (int jp = 0; jp < 4; ++jp) {
;                 const u32x2 lo = *(const LAS u32x2*)(vts + (16 * dvt + fr) * 136 + 32 * jp + 4 * fq);
;                 const u32x2 hi = *(const LAS u32x2*)(vts + (16 * dvt + fr) * 136 + 32 * jp + 16 + 4 * fq);
;                 u32x4 bv; bv[0] = lo.x; bv[1] = lo.y; bv[2] = hi.x; bv[3] = hi.y;
;                 o = __builtin_amdgcn_mfma_f32_16x16x32_bf16(pa[jp], __builtin_bit_cast(bf16x8, bv), o, 0, 0, 0);
;             }
; #pragma unroll
;             for (int ks = 0; ks < 2; ++ks) {
;                 const bf16x8 sf = *(const LAS bf16x8*)(sfs + (16 * dvt + fr) * 72 + 32 * ks + 8 * fq);
;                 const bf16x8 sb = *(const LAS bf16x8*)(sbs + (16 * dvt + fr) * 72 + 32 * ks + 8 * fq);
;                 o = __builtin_amdgcn_mfma_f32_16x16x32_bf16(qF[ks], sf, o, 0, 0, 0);
;                 o = __builtin_amdgcn_mfma_f32_16x16x32_bf16(qB[ks], sb, o, 0, 0, 0);
;             }
;             O[dvt] = o;
;             __builtin_amdgcn_sched_barrier(0);
;         }
; #pragma unroll
;         for (int r = 0; r < 4; ++r) {
;             float sm = 0.f;
; #pragma unroll
;             for (int dvt = 0; dvt < 8; ++dvt) sm += O[dvt][r];
;             const float mu = sum16(sm) * (1.f / DV);
;             float q2 = 0.f;
; #pragma unroll
;             for (int dvt = 0; dvt < 8; ++dvt) { const float dd = O[dvt][r] - mu; q2 += dd * dd; }
;             const float rstd = rsqrtf(sum16(q2) * (1.f / DV) + EPS);
; #pragma unroll
;             for (int dvt = 0; dvt < 8; ++dvt) os[(16 * w + 4 * fq + r) * 136 + 16 * dvt + fr] = f2bf((O[dvt][r] - mu) * rstd);
;         }
	v_mfma_f32_16x16x32_bf16 v[42:45], v[42:45], v[62:65], v[46:49]
	s_nop 5
	v_add_f32_e64 v46, v74, 0
	v_add_f32_e64 v47, v75, 0
	v_mov_b32_e32 v50, v86
	v_pk_add_f32 v[46:47], v[46:47], v[78:79]
	v_mov_b32_e32 v51, v82
	v_pk_add_f32 v[46:47], v[46:47], v[82:83]
	v_mov_b32_e32 v82, v87
	v_pk_add_f32 v[46:47], v[46:47], v[86:87]
	v_mov_b32_e32 v52, v94
	v_pk_add_f32 v[46:47], v[46:47], v[90:91]
	v_mov_b32_e32 v53, v90
	v_pk_add_f32 v[46:47], v[46:47], v[94:95]
	v_mov_b32_e32 v90, v95
	v_pk_add_f32 v[46:47], v[46:47], v[98:99]
	v_mov_b32_e32 v54, v42
	v_pk_add_f32 v[46:47], v[46:47], v[42:43]
	ds_bpermute_b32 v48, v127, v46
	ds_bpermute_b32 v49, v127, v47
	v_mov_b32_e32 v55, v98
	v_mov_b32_e32 v98, v43
	s_mov_b32 s2, 0x358637bd
	s_add_i32 vcc_hi, vcc_hi, s34
	s_waitcnt lgkmcnt(0)
	v_pk_add_f32 v[46:47], v[46:47], v[48:49]
	ds_bpermute_b32 v48, v130, v46
	ds_bpermute_b32 v49, v130, v47
	s_add_i32 s61, s61, s60
	s_cmp_lg_u32 s37, s39
	s_waitcnt lgkmcnt(0)
	v_pk_add_f32 v[46:47], v[46:47], v[48:49]
	ds_bpermute_b32 v48, v131, v46
	ds_bpermute_b32 v49, v131, v47
	s_waitcnt lgkmcnt(0)
	v_pk_add_f32 v[46:47], v[46:47], v[48:49]
	ds_bpermute_b32 v48, v132, v46
	ds_bpermute_b32 v49, v132, v47
	s_waitcnt lgkmcnt(0)
	v_pk_add_f32 v[46:47], v[46:47], v[48:49]
	s_nop 0
	v_pk_mul_f32 v[48:49], v[46:47], s[18:19] op_sel_hi:[1,0]
	v_pk_fma_f32 v[64:65], v[46:47], s[18:19], v[78:79] op_sel_hi:[1,0,1] neg_lo:[1,0,0] neg_hi:[1,0,0]
	v_pk_add_f32 v[50:51], v[50:51], v[48:49] op_sel_hi:[1,0] neg_lo:[0,1] neg_hi:[0,1]
	v_pk_add_f32 v[68:69], v[82:83], v[48:49] op_sel:[0,1] neg_lo:[0,1] neg_hi:[0,1]
	v_pk_fma_f32 v[56:57], v[46:47], s[18:19], v[74:75] op_sel_hi:[1,0,1] neg_lo:[1,0,0] neg_hi:[1,0,0]
	v_pk_mul_f32 v[58:59], v[50:51], v[50:51]
	v_pk_mul_f32 v[46:47], v[64:65], v[64:65]
	v_pk_mul_f32 v[70:71], v[68:69], v[68:69]
	v_pk_add_f32 v[52:53], v[52:53], v[48:49] op_sel_hi:[1,0] neg_lo:[0,1] neg_hi:[0,1]
	v_pk_fma_f32 v[66:67], v[56:57], v[56:57], v[46:47]
	v_pk_add_f32 v[46:47], v[90:91], v[48:49] op_sel:[0,1] neg_lo:[0,1] neg_hi:[0,1]
	v_mov_b32_e32 v75, v58
	v_mov_b32_e32 v58, v71
	v_pk_mul_f32 v[60:61], v[52:53], v[52:53]
	v_pk_mul_f32 v[72:73], v[46:47], v[46:47]
	v_mov_b32_e32 v74, v70
	v_pk_add_f32 v[58:59], v[58:59], v[66:67] op_sel:[0,1] op_sel_hi:[1,0]
	v_pk_add_f32 v[54:55], v[54:55], v[48:49] op_sel_hi:[1,0] neg_lo:[0,1] neg_hi:[0,1]
	v_pk_add_f32 v[42:43], v[98:99], v[48:49] op_sel:[0,1] neg_lo:[0,1] neg_hi:[0,1]
	v_pk_add_f32 v[58:59], v[74:75], v[58:59]
	v_mov_b32_e32 v66, v73
	v_mov_b32_e32 v67, v61
	v_pk_mul_f32 v[62:63], v[54:55], v[54:55]
	v_pk_mul_f32 v[48:49], v[42:43], v[42:43]
	v_pk_add_f32 v[58:59], v[66:67], v[58:59]
	v_mov_b32_e32 v73, v60
	v_pk_add_f32 v[58:59], v[72:73], v[58:59]
	v_mov_b32_e32 v60, v49
	v_mov_b32_e32 v61, v63
	v_pk_add_f32 v[58:59], v[60:61], v[58:59]
	v_mov_b32_e32 v49, v62
	v_pk_add_f32 v[48:49], v[48:49], v[58:59]
	ds_bpermute_b32 v59, v127, v49
	ds_bpermute_b32 v58, v127, v48
	s_waitcnt lgkmcnt(0)
	v_pk_add_f32 v[48:49], v[48:49], v[58:59]
	ds_bpermute_b32 v59, v130, v49
	ds_bpermute_b32 v58, v130, v48
	s_waitcnt lgkmcnt(0)
	v_pk_add_f32 v[48:49], v[48:49], v[58:59]
	ds_bpermute_b32 v59, v131, v49
	ds_bpermute_b32 v58, v131, v48
	s_waitcnt lgkmcnt(0)
	v_pk_add_f32 v[48:49], v[48:49], v[58:59]
	ds_bpermute_b32 v59, v132, v49
	ds_bpermute_b32 v58, v132, v48
	s_waitcnt lgkmcnt(0)
	v_pk_add_f32 v[48:49], v[48:49], v[58:59]
	v_mov_b64_e32 v[58:59], s[2:3]
	v_pk_fma_f32 v[48:49], v[48:49], s[18:19], v[58:59] op_sel_hi:[1,0,0]
	s_mov_b32 s2, 0xfcc8000
	v_mul_f32_e32 v60, 0x4b800000, v49
	v_cmp_gt_f32_e64 s[74:75], s33, v49
	s_nop 1
	v_cndmask_b32_e64 v49, v49, v60, s[74:75]
	v_rsq_f32_e32 v49, v49
	s_nop 0
	v_mul_f32_e32 v60, 0x45800000, v49
	v_cndmask_b32_e64 v49, v49, v60, s[74:75]
	v_mul_f32_e32 v50, v50, v49
	v_cvt_pk_bf16_f32 v50, v50, s0
	ds_write_b16 v249, v50 offset:96
	v_mul_f32_e32 v50, v53, v49
	v_cvt_pk_bf16_f32 v50, v50, s0
	v_mul_f32_e32 v56, v56, v49
	ds_write_b16 v249, v50 offset:128
	v_mul_f32_e32 v50, v52, v49
	v_cvt_pk_bf16_f32 v56, v56, s0
	v_cvt_pk_bf16_f32 v50, v50, s0
	ds_write_b16 v249, v56
	v_mul_f32_e32 v56, v64, v49
	v_mul_f32_e32 v51, v51, v49
	ds_write_b16 v249, v50 offset:160
	v_mul_f32_e32 v50, v55, v49
	v_mul_f32_e32 v52, v54, v49
	v_mul_f32_e32 v49, 0x4b800000, v48
	v_cmp_gt_f32_e64 s[74:75], s33, v48
	v_cvt_pk_bf16_f32 v51, v51, s0
	v_cvt_pk_bf16_f32 v50, v50, s0
	v_cndmask_b32_e64 v48, v48, v49, s[74:75]
	v_rsq_f32_e32 v53, v48
	v_pk_add_f32 v[48:49], v[76:77], 0 op_sel_hi:[1,0]
	ds_write_b16 v249, v51 offset:64
	v_pk_add_f32 v[48:49], v[48:49], v[80:81]
	ds_write_b16 v249, v50 offset:192
	v_pk_add_f32 v[48:49], v[48:49], v[84:85]
	v_cvt_pk_bf16_f32 v52, v52, s0
	v_pk_add_f32 v[48:49], v[48:49], v[88:89]
	ds_write_b16 v249, v52 offset:224
	v_pk_add_f32 v[48:49], v[48:49], v[92:93]
	v_mul_f32_e32 v52, 0x45800000, v53
	v_pk_add_f32 v[48:49], v[48:49], v[96:97]
	v_cndmask_b32_e64 v82, v53, v52, s[74:75]
	v_pk_add_f32 v[48:49], v[48:49], v[100:101]
	v_mul_f32_e32 v52, v57, v82
	v_pk_add_f32 v[48:49], v[48:49], v[44:45]
	ds_bpermute_b32 v50, v127, v48
	ds_bpermute_b32 v51, v127, v49
	v_cvt_pk_bf16_f32 v52, v52, s0
	ds_write_b16 v249, v52 offset:272
	v_mul_f32_e32 v52, v65, v82
	v_cvt_pk_bf16_f32 v83, v52, s0
	s_waitcnt lgkmcnt(1)
	v_pk_add_f32 v[48:49], v[48:49], v[50:51]
	ds_bpermute_b32 v50, v130, v48
	ds_bpermute_b32 v51, v130, v49
	v_mov_b32_e32 v52, v88
	v_mov_b32_e32 v53, v84
	v_mov_b32_e32 v84, v89
	v_mov_b32_e32 v54, v96
	s_waitcnt lgkmcnt(0)
	v_pk_add_f32 v[48:49], v[48:49], v[50:51]
	ds_bpermute_b32 v50, v131, v48
	ds_bpermute_b32 v51, v131, v49
	v_mov_b32_e32 v55, v92
	v_mov_b32_e32 v92, v97
	v_cvt_pk_bf16_f32 v56, v56, s0
	ds_write_b16 v249, v56 offset:32
	s_waitcnt lgkmcnt(1)
; __device__ __forceinline__ bf16_t f2bf(float f) { return (bf16_t)(pk2(f, 0.f) & 0xffffu); }
; __device__ __forceinline__ void ret_out_phase(const Args& A, Frame& F, int l, bool lastl, bf16_t* ARET, bf16_t* ALRU) {
;     ...
; #pragma unroll
;         for (int r = 0; r < 4; ++r) {
;             float sm = 0.f;
; #pragma unroll
;             for (int dvt = 0; dvt < 8; ++dvt) sm += O[dvt][r];
;             const float mu = sum16(sm) * (1.f / DV);
;             float q2 = 0.f;
; #pragma unroll
;             for (int dvt = 0; dvt < 8; ++dvt) { const float dd = O[dvt][r] - mu; q2 += dd * dd; }
;             const float rstd = rsqrtf(sum16(q2) * (1.f / DV) + EPS);
; #pragma unroll
;             for (int dvt = 0; dvt < 8; ++dvt) os[(16 * w + 4 * fq + r) * 136 + 16 * dvt + fr] = f2bf((O[dvt][r] - mu) * rstd);
;         }
;         __builtin_amdgcn_fence(__ATOMIC_RELEASE, "workgroup"); __builtin_amdgcn_wave_barrier(); __builtin_amdgcn_fence(__ATOMIC_ACQUIRE, "workgroup");
;         {
;             const int rr = 16 * w + (lane >> 2), cc = (lane & 3) * 32;
;             const size_t go = (rowbase + rr) * D + 128 * h + cc;
	v_pk_add_f32 v[48:49], v[48:49], v[50:51]
	ds_bpermute_b32 v50, v132, v48
	ds_bpermute_b32 v51, v132, v49
	v_mov_b32_e32 v56, v44
	v_mov_b32_e32 v57, v100
	v_mov_b32_e32 v100, v45
	v_mul_f32_e32 v47, v47, v82
	s_waitcnt lgkmcnt(0)
	v_pk_add_f32 v[48:49], v[48:49], v[50:51]
	v_cvt_pk_bf16_f32 v47, v47, s0
	v_pk_mul_f32 v[50:51], v[48:49], s[18:19] op_sel_hi:[1,0]
	v_pk_fma_f32 v[66:67], v[48:49], s[18:19], v[76:77] op_sel_hi:[1,0,1] neg_lo:[1,0,0] neg_hi:[1,0,0]
	v_pk_add_f32 v[52:53], v[52:53], v[50:51] op_sel_hi:[1,0] neg_lo:[0,1] neg_hi:[0,1]
	v_pk_fma_f32 v[48:49], v[48:49], s[18:19], v[80:81] op_sel_hi:[1,0,1] neg_lo:[1,0,0] neg_hi:[1,0,0]
	v_pk_add_f32 v[72:73], v[84:85], v[50:51] op_sel:[0,1] neg_lo:[0,1] neg_hi:[0,1]
	v_pk_mul_f32 v[60:61], v[52:53], v[52:53]
	v_pk_mul_f32 v[70:71], v[48:49], v[48:49]
	v_pk_mul_f32 v[74:75], v[72:73], v[72:73]
	v_pk_add_f32 v[54:55], v[54:55], v[50:51] op_sel_hi:[1,0] neg_lo:[0,1] neg_hi:[0,1]
	v_pk_fma_f32 v[70:71], v[66:67], v[66:67], v[70:71]
	v_pk_add_f32 v[76:77], v[92:93], v[50:51] op_sel:[0,1] neg_lo:[0,1] neg_hi:[0,1]
	v_mov_b32_e32 v81, v60
	v_mov_b32_e32 v60, v75
	v_pk_mul_f32 v[62:63], v[54:55], v[54:55]
	v_pk_mul_f32 v[78:79], v[76:77], v[76:77]
	v_mov_b32_e32 v80, v74
	v_pk_add_f32 v[60:61], v[60:61], v[70:71] op_sel:[0,1] op_sel_hi:[1,0]
	v_pk_add_f32 v[56:57], v[56:57], v[50:51] op_sel_hi:[1,0] neg_lo:[0,1] neg_hi:[0,1]
	v_pk_add_f32 v[44:45], v[100:101], v[50:51] op_sel:[0,1] neg_lo:[0,1] neg_hi:[0,1]
	v_pk_add_f32 v[60:61], v[80:81], v[60:61]
	v_mov_b32_e32 v70, v79
	v_mov_b32_e32 v71, v63
	v_pk_mul_f32 v[64:65], v[56:57], v[56:57]
	v_pk_mul_f32 v[50:51], v[44:45], v[44:45]
	v_pk_add_f32 v[60:61], v[70:71], v[60:61]
	v_mov_b32_e32 v79, v62
	v_pk_add_f32 v[60:61], v[78:79], v[60:61]
	v_mov_b32_e32 v62, v51
	v_mov_b32_e32 v63, v65
	v_pk_add_f32 v[60:61], v[62:63], v[60:61]
	v_mov_b32_e32 v51, v64
	v_pk_add_f32 v[50:51], v[50:51], v[60:61]
	ds_bpermute_b32 v61, v127, v51
	ds_bpermute_b32 v60, v127, v50
	v_mul_f32_e32 v62, v69, v82
	v_cvt_pk_bf16_f32 v62, v62, s0
	ds_write_b16 v249, v62 offset:336
	v_mul_f32_e32 v62, v68, v82
	s_waitcnt lgkmcnt(1)
	v_pk_add_f32 v[50:51], v[50:51], v[60:61]
	ds_bpermute_b32 v61, v130, v51
	ds_bpermute_b32 v60, v130, v50
	v_cvt_pk_bf16_f32 v62, v62, s0
	v_mul_f32_e32 v46, v46, v82
	ds_write_b16 v249, v62 offset:368
	ds_write_b16 v249, v47 offset:400
	s_waitcnt lgkmcnt(2)
	v_pk_add_f32 v[50:51], v[50:51], v[60:61]
	ds_bpermute_b32 v61, v131, v51
	ds_bpermute_b32 v60, v131, v50
	v_cvt_pk_bf16_f32 v62, v46, s0
	v_mul_f32_e32 v43, v43, v82
	v_cvt_pk_bf16_f32 v43, v43, s0
	ds_write_b16 v249, v43 offset:464
	s_waitcnt lgkmcnt(1)
	v_pk_add_f32 v[46:47], v[50:51], v[60:61]
	ds_bpermute_b32 v51, v132, v47
	ds_bpermute_b32 v50, v132, v46
	v_mul_f32_e32 v42, v42, v82
	v_cvt_pk_bf16_f32 v42, v42, s0
	ds_write_b16 v249, v42 offset:496
	ds_write_b16 v249, v83 offset:304
	s_waitcnt lgkmcnt(2)
	v_pk_add_f32 v[46:47], v[46:47], v[50:51]
	ds_write_b16 v249, v62 offset:432
	v_pk_fma_f32 v[46:47], v[46:47], s[18:19], v[58:59] op_sel_hi:[1,0,0]
	s_nop 0
	v_mul_f32_e32 v43, 0x4b800000, v47
	v_cmp_gt_f32_e64 s[74:75], s33, v47
	s_nop 1
	v_cndmask_b32_e64 v43, v47, v43, s[74:75]
	v_rsq_f32_e32 v43, v43
	s_nop 0
	v_mul_f32_e32 v42, 0x45800000, v43
	v_cndmask_b32_e64 v42, v43, v42, s[74:75]
	v_mul_f32_e32 v43, v66, v42
	v_cvt_pk_bf16_f32 v43, v43, s0
	ds_write_b16 v249, v43 offset:544
	v_mul_f32_e32 v43, v48, v42
	v_cvt_pk_bf16_f32 v43, v43, s0
	ds_write_b16 v249, v43 offset:576
	v_mul_f32_e32 v43, v53, v42
	v_cvt_pk_bf16_f32 v43, v43, s0
	ds_write_b16 v249, v43 offset:608
	v_mul_f32_e32 v43, v52, v42
	v_cvt_pk_bf16_f32 v43, v43, s0
	ds_write_b16 v249, v43 offset:640
	v_mul_f32_e32 v43, v55, v42
	v_cvt_pk_bf16_f32 v43, v43, s0
	ds_write_b16 v249, v43 offset:672
	v_mul_f32_e32 v43, v54, v42
	v_cvt_pk_bf16_f32 v43, v43, s0
	ds_write_b16 v249, v43 offset:704
	v_mul_f32_e32 v43, v57, v42
	v_cvt_pk_bf16_f32 v43, v43, s0
	ds_write_b16 v249, v43 offset:736
	v_mul_f32_e32 v43, 0x4b800000, v46
	v_cmp_gt_f32_e64 s[74:75], s33, v46
	v_mul_f32_e32 v42, v56, v42
	v_cvt_pk_bf16_f32 v42, v42, s0
	v_cndmask_b32_e64 v43, v46, v43, s[74:75]
	v_rsq_f32_e32 v43, v43
	ds_write_b16 v249, v42 offset:768
	v_mul_f32_e32 v42, 0x45800000, v43
	v_cndmask_b32_e64 v42, v43, v42, s[74:75]
	v_mul_f32_e32 v43, v67, v42
	v_cvt_pk_bf16_f32 v43, v43, s0
	ds_write_b16 v249, v43 offset:816
	v_mul_f32_e32 v43, v49, v42
	v_cvt_pk_bf16_f32 v43, v43, s0
	ds_write_b16 v249, v43 offset:848
	v_mul_f32_e32 v43, v73, v42
	v_cvt_pk_bf16_f32 v43, v43, s0
	ds_write_b16 v249, v43 offset:880
	v_mul_f32_e32 v43, v72, v42
	v_cvt_pk_bf16_f32 v43, v43, s0
	ds_write_b16 v249, v43 offset:912
	v_mul_f32_e32 v43, v77, v42
	v_cvt_pk_bf16_f32 v43, v43, s0
	ds_write_b16 v249, v43 offset:944
	v_mul_f32_e32 v43, v76, v42
	v_cvt_pk_bf16_f32 v43, v43, s0
	ds_write_b16 v249, v43 offset:976
	v_mul_f32_e32 v43, v45, v42
	v_mul_f32_e32 v42, v44, v42
	v_cvt_pk_bf16_f32 v43, v43, s0
	v_cvt_pk_bf16_f32 v42, v42, s0
	ds_write_b16 v249, v43 offset:1008
	ds_write_b16 v249, v42 offset:1040
	v_lshl_add_u64 v[42:43], s[8:9], 0, v[124:125]
	v_lshlrev_b64 v[42:43], 10, v[42:43]
	v_or_b32_e32 v42, v42, v126
	v_or_b32_e32 v42, s82, v42
	v_lshlrev_b64 v[54:55], 1, v[42:43]
	v_lshl_add_u64 v[42:43], s[50:51], 0, v[54:55]
	s_waitcnt lgkmcnt(0)
; #define LAS __attribute__((address_space(3)))
; __device__ __forceinline__ unsigned pk2(float lo, float hi) { const f32x2_t v = {lo, hi}; const bf16v2_t b = __builtin_convertvector(v, bf16v2_t); return __builtin_bit_cast(unsigned, b); }
; __device__ __forceinline__ float bflo(unsigned u) { return __uint_as_float(u << 16); }
; __device__ __forceinline__ float bfhi(unsigned u) { return __uint_as_float(u & 0xffff0000u); }
; __device__ __forceinline__ void ret_out_phase(const Args& A, Frame& F, int l, bool lastl, bf16_t* ARET, bf16_t* ALRU) {
;     ...
;         {
;             const int rr = 16 * w + (lane >> 2), cc = (lane & 3) * 32;
;             const size_t go = (rowbase + rr) * D + 128 * h + cc;
; #pragma unroll
;             for (int i = 0; i < 4; ++i) {
;                 const u32x4 ov = *(const LAS u32x4*)(os + rr * 136 + cc + 8 * i);
;                 const u32x4 gv = *(const u32x4*)(WSB(WS_SG) + go + 8 * i);
;                 u32x4 rv;
; #pragma unroll
;                 for (int e = 0; e < 4; ++e) rv[e] = pk2(bflo(ov[e]) * bflo(gv[e]), bfhi(ov[e]) * bfhi(gv[e]));
;                 *(u32x4*)(ARET + go + 8 * i) = rv;
;             }
;         }
; #pragma unroll
;         for (int i = 0; i < 4; ++i) {
;             const int u = tid + i * NTHREADS, r = u >> 4, c8 = (u & 15) * 8;
;             const size_t o = (rowbase + r) * D + 128 * h + c8;
;             const u32x4 hf = *(const u32x4*)(WSB(WS_HF) + o), hb = *(const u32x4*)(WSB(WS_HB) + o), gg = *(const u32x4*)(WSB(WS_GG) + o);
	v_add_u32_e32 v129, s8, v124
	v_lshlrev_b32_e32 v129, 11, v129
	v_or_b32_e32 v100, s82, v126
	v_lshl_or_b32 v129, v100, 1, v129
	v_or_b32_e32 v100, s82, v104
	v_add_u32_e32 v141, s8, v106
	v_lshlrev_b32_e32 v141, 11, v141
	v_lshl_or_b32 v141, v100, 1, v141
	v_add_u32_e32 v250, s8, v108
	v_lshlrev_b32_e32 v250, 11, v250
	v_lshl_or_b32 v250, v100, 1, v250
	v_add_u32_e32 v251, s8, v110
	v_lshlrev_b32_e32 v251, 11, v251
	v_lshl_or_b32 v251, v100, 1, v251
	v_add_u32_e32 v252, s8, v112
	v_lshlrev_b32_e32 v252, 11, v252
	v_lshl_or_b32 v252, v100, 1, v252
	global_load_dwordx4 v[56:59], v129, s[50:51]
	global_load_dwordx4 v[60:63], v129, s[50:51] offset:16
	global_load_dwordx4 v[64:67], v129, s[50:51] offset:32
	global_load_dwordx4 v[68:71], v129, s[50:51] offset:48
	global_load_dwordx4 v[72:75], v141, s[10:11]
	global_load_dwordx4 v[76:79], v141, s[12:13]
	global_load_dwordx4 v[80:83], v141, s[14:15]
	global_load_dwordx4 v[84:87], v250, s[10:11]
	global_load_dwordx4 v[88:91], v250, s[12:13]
	global_load_dwordx4 v[92:95], v250, s[14:15]
	ds_read_b128 v[96:99], v133
	ds_read_b128 v[44:47], v133 offset:16
	s_waitcnt vmcnt(9) lgkmcnt(1)
	v_lshlrev_b32_e32 v100, 16, v96
	v_and_b32_e32 v101, 0xffff0000, v96
	v_lshlrev_b32_e32 v52, 16, v56
	v_and_b32_e32 v53, 0xffff0000, v56
	v_pk_mul_f32 v[100:101], v[100:101], v[52:53]
	s_nop 0
	v_cvt_pk_bf16_f32 v56, v100, v101
	v_lshlrev_b32_e32 v100, 16, v97
	v_and_b32_e32 v101, 0xffff0000, v97
	v_lshlrev_b32_e32 v52, 16, v57
	v_and_b32_e32 v53, 0xffff0000, v57
	v_pk_mul_f32 v[100:101], v[100:101], v[52:53]
	s_nop 0
	v_cvt_pk_bf16_f32 v57, v100, v101
	v_lshlrev_b32_e32 v100, 16, v98
	v_and_b32_e32 v101, 0xffff0000, v98
	v_lshlrev_b32_e32 v52, 16, v58
	v_and_b32_e32 v53, 0xffff0000, v58
	v_pk_mul_f32 v[100:101], v[100:101], v[52:53]
	s_nop 0
	v_cvt_pk_bf16_f32 v58, v100, v101
	v_lshlrev_b32_e32 v100, 16, v99
	v_and_b32_e32 v101, 0xffff0000, v99
	v_lshlrev_b32_e32 v52, 16, v59
	v_and_b32_e32 v53, 0xffff0000, v59
	v_pk_mul_f32 v[100:101], v[100:101], v[52:53]
	s_nop 0
	v_cvt_pk_bf16_f32 v59, v100, v101
	global_store_dwordx4 v129, v[56:59], s[88:89]
	s_waitcnt vmcnt(9) lgkmcnt(0)
	v_lshlrev_b32_e32 v100, 16, v44
	v_and_b32_e32 v101, 0xffff0000, v44
	v_lshlrev_b32_e32 v52, 16, v60
	v_and_b32_e32 v53, 0xffff0000, v60
	v_pk_mul_f32 v[100:101], v[100:101], v[52:53]
	s_nop 0
	v_cvt_pk_bf16_f32 v60, v100, v101
	v_lshlrev_b32_e32 v100, 16, v45
	v_and_b32_e32 v101, 0xffff0000, v45
	v_lshlrev_b32_e32 v52, 16, v61
	v_and_b32_e32 v53, 0xffff0000, v61
	v_pk_mul_f32 v[100:101], v[100:101], v[52:53]
	s_nop 0
	v_cvt_pk_bf16_f32 v61, v100, v101
	v_lshlrev_b32_e32 v100, 16, v46
	v_and_b32_e32 v101, 0xffff0000, v46
	v_lshlrev_b32_e32 v52, 16, v62
	v_and_b32_e32 v53, 0xffff0000, v62
	v_pk_mul_f32 v[100:101], v[100:101], v[52:53]
	s_nop 0
	v_cvt_pk_bf16_f32 v62, v100, v101
	v_lshlrev_b32_e32 v100, 16, v47
	v_and_b32_e32 v101, 0xffff0000, v47
	v_lshlrev_b32_e32 v52, 16, v63
	v_and_b32_e32 v53, 0xffff0000, v63
	v_pk_mul_f32 v[100:101], v[100:101], v[52:53]
	s_nop 0
	v_cvt_pk_bf16_f32 v63, v100, v101
	global_store_dwordx4 v129, v[60:63], s[88:89] offset:16
	ds_read_b128 v[96:99], v133 offset:32
	ds_read_b128 v[44:47], v133 offset:48
	s_waitcnt vmcnt(9) lgkmcnt(1)
	v_lshlrev_b32_e32 v100, 16, v96
	v_and_b32_e32 v101, 0xffff0000, v96
	v_lshlrev_b32_e32 v52, 16, v64
	v_and_b32_e32 v53, 0xffff0000, v64
	v_pk_mul_f32 v[100:101], v[100:101], v[52:53]
	s_nop 0
	v_cvt_pk_bf16_f32 v64, v100, v101
	v_lshlrev_b32_e32 v100, 16, v97
	v_and_b32_e32 v101, 0xffff0000, v97
	v_lshlrev_b32_e32 v52, 16, v65
	v_and_b32_e32 v53, 0xffff0000, v65
	v_pk_mul_f32 v[100:101], v[100:101], v[52:53]
	s_nop 0
	v_cvt_pk_bf16_f32 v65, v100, v101
	v_lshlrev_b32_e32 v100, 16, v98
	v_and_b32_e32 v101, 0xffff0000, v98
	v_lshlrev_b32_e32 v52, 16, v66
	v_and_b32_e32 v53, 0xffff0000, v66
	v_pk_mul_f32 v[100:101], v[100:101], v[52:53]
	s_nop 0
	v_cvt_pk_bf16_f32 v66, v100, v101
	v_lshlrev_b32_e32 v100, 16, v99
	v_and_b32_e32 v101, 0xffff0000, v99
	v_lshlrev_b32_e32 v52, 16, v67
	v_and_b32_e32 v53, 0xffff0000, v67
	v_pk_mul_f32 v[100:101], v[100:101], v[52:53]
	s_nop 0
	v_cvt_pk_bf16_f32 v67, v100, v101
	global_store_dwordx4 v129, v[64:67], s[88:89] offset:32
	s_waitcnt vmcnt(9) lgkmcnt(0)
	v_lshlrev_b32_e32 v100, 16, v44
	v_and_b32_e32 v101, 0xffff0000, v44
	v_lshlrev_b32_e32 v52, 16, v68
	v_and_b32_e32 v53, 0xffff0000, v68
	v_pk_mul_f32 v[100:101], v[100:101], v[52:53]
	s_nop 0
	v_cvt_pk_bf16_f32 v68, v100, v101
	v_lshlrev_b32_e32 v100, 16, v45
	v_and_b32_e32 v101, 0xffff0000, v45
	v_lshlrev_b32_e32 v52, 16, v69
	v_and_b32_e32 v53, 0xffff0000, v69
	v_pk_mul_f32 v[100:101], v[100:101], v[52:53]
	s_nop 0
	v_cvt_pk_bf16_f32 v69, v100, v101
	v_lshlrev_b32_e32 v100, 16, v46
	v_and_b32_e32 v101, 0xffff0000, v46
	v_lshlrev_b32_e32 v52, 16, v70
	v_and_b32_e32 v53, 0xffff0000, v70
	v_pk_mul_f32 v[100:101], v[100:101], v[52:53]
	s_nop 0
	v_cvt_pk_bf16_f32 v70, v100, v101
	v_lshlrev_b32_e32 v100, 16, v47
	v_and_b32_e32 v101, 0xffff0000, v47
	v_lshlrev_b32_e32 v52, 16, v71
	v_and_b32_e32 v53, 0xffff0000, v71
	v_pk_mul_f32 v[100:101], v[100:101], v[52:53]
	s_nop 0
	v_cvt_pk_bf16_f32 v71, v100, v101
	global_store_dwordx4 v129, v[68:71], s[88:89] offset:48
	s_nop 1
	global_load_dwordx4 v[56:59], v251, s[10:11]
	global_load_dwordx4 v[60:63], v251, s[12:13]
	global_load_dwordx4 v[64:67], v251, s[14:15]
	global_load_dwordx4 v[68:71], v252, s[10:11]
	global_load_dwordx4 v[44:47], v252, s[12:13]
	global_load_dwordx4 v[48:51], v252, s[14:15]
	s_waitcnt vmcnt(13)
; __device__ __forceinline__ unsigned pk2(float lo, float hi) { const f32x2_t v = {lo, hi}; const bf16v2_t b = __builtin_convertvector(v, bf16v2_t); return __builtin_bit_cast(unsigned, b); }
; __device__ __forceinline__ float bflo(unsigned u) { return __uint_as_float(u << 16); }
; __device__ __forceinline__ float bfhi(unsigned u) { return __uint_as_float(u & 0xffff0000u); }
; __device__ __forceinline__ void ret_out_phase(const Args& A, Frame& F, int l, bool lastl, bf16_t* ARET, bf16_t* ALRU) {
;     ...
; #pragma unroll
;         for (int i = 0; i < 4; ++i) {
;             const int u = tid + i * NTHREADS, r = u >> 4, c8 = (u & 15) * 8;
;             const size_t o = (rowbase + r) * D + 128 * h + c8;
;             const u32x4 hf = *(const u32x4*)(WSB(WS_HF) + o), hb = *(const u32x4*)(WSB(WS_HB) + o), gg = *(const u32x4*)(WSB(WS_GG) + o);
;             u32x4 ov;
; #pragma unroll
;             for (int e = 0; e < 4; ++e) ov[e] = pk2((bflo(hf[e]) + bflo(hb[e])) * bflo(gg[e]), (bfhi(hf[e]) + bfhi(hb[e])) * bfhi(gg[e]));
;             *(u32x4*)(ALRU + o) = ov;
;         }
;     }
	v_lshlrev_b32_e32 v100, 16, v72
	v_and_b32_e32 v101, 0xffff0000, v72
	v_lshlrev_b32_e32 v52, 16, v76
	v_and_b32_e32 v53, 0xffff0000, v76
	v_pk_add_f32 v[100:101], v[100:101], v[52:53]
	v_lshlrev_b32_e32 v52, 16, v80
	v_and_b32_e32 v53, 0xffff0000, v80
	v_pk_mul_f32 v[100:101], v[100:101], v[52:53]
	s_nop 0
	v_cvt_pk_bf16_f32 v72, v100, v101
	v_lshlrev_b32_e32 v100, 16, v73
	v_and_b32_e32 v101, 0xffff0000, v73
	v_lshlrev_b32_e32 v52, 16, v77
	v_and_b32_e32 v53, 0xffff0000, v77
	v_pk_add_f32 v[100:101], v[100:101], v[52:53]
	v_lshlrev_b32_e32 v52, 16, v81
	v_and_b32_e32 v53, 0xffff0000, v81
	v_pk_mul_f32 v[100:101], v[100:101], v[52:53]
	s_nop 0
	v_cvt_pk_bf16_f32 v73, v100, v101
	v_lshlrev_b32_e32 v100, 16, v74
	v_and_b32_e32 v101, 0xffff0000, v74
	v_lshlrev_b32_e32 v52, 16, v78
	v_and_b32_e32 v53, 0xffff0000, v78
	v_pk_add_f32 v[100:101], v[100:101], v[52:53]
	v_lshlrev_b32_e32 v52, 16, v82
	v_and_b32_e32 v53, 0xffff0000, v82
	v_pk_mul_f32 v[100:101], v[100:101], v[52:53]
	s_nop 0
	v_cvt_pk_bf16_f32 v74, v100, v101
	v_lshlrev_b32_e32 v100, 16, v75
	v_and_b32_e32 v101, 0xffff0000, v75
	v_lshlrev_b32_e32 v52, 16, v79
	v_and_b32_e32 v53, 0xffff0000, v79
	v_pk_add_f32 v[100:101], v[100:101], v[52:53]
	v_lshlrev_b32_e32 v52, 16, v83
	v_and_b32_e32 v53, 0xffff0000, v83
	v_pk_mul_f32 v[100:101], v[100:101], v[52:53]
	s_nop 0
	v_cvt_pk_bf16_f32 v75, v100, v101
	global_store_dwordx4 v141, v[72:75], s[90:91]
	s_waitcnt vmcnt(11)
	v_lshlrev_b32_e32 v100, 16, v84
	v_and_b32_e32 v101, 0xffff0000, v84
	v_lshlrev_b32_e32 v52, 16, v88
	v_and_b32_e32 v53, 0xffff0000, v88
	v_pk_add_f32 v[100:101], v[100:101], v[52:53]
	v_lshlrev_b32_e32 v52, 16, v92
	v_and_b32_e32 v53, 0xffff0000, v92
	v_pk_mul_f32 v[100:101], v[100:101], v[52:53]
	s_nop 0
	v_cvt_pk_bf16_f32 v84, v100, v101
	v_lshlrev_b32_e32 v100, 16, v85
	v_and_b32_e32 v101, 0xffff0000, v85
	v_lshlrev_b32_e32 v52, 16, v89
	v_and_b32_e32 v53, 0xffff0000, v89
	v_pk_add_f32 v[100:101], v[100:101], v[52:53]
	v_lshlrev_b32_e32 v52, 16, v93
	v_and_b32_e32 v53, 0xffff0000, v93
	v_pk_mul_f32 v[100:101], v[100:101], v[52:53]
	s_nop 0
	v_cvt_pk_bf16_f32 v85, v100, v101
	v_lshlrev_b32_e32 v100, 16, v86
	v_and_b32_e32 v101, 0xffff0000, v86
	v_lshlrev_b32_e32 v52, 16, v90
	v_and_b32_e32 v53, 0xffff0000, v90
	v_pk_add_f32 v[100:101], v[100:101], v[52:53]
	v_lshlrev_b32_e32 v52, 16, v94
	v_and_b32_e32 v53, 0xffff0000, v94
	v_pk_mul_f32 v[100:101], v[100:101], v[52:53]
	s_nop 0
	v_cvt_pk_bf16_f32 v86, v100, v101
	v_lshlrev_b32_e32 v100, 16, v87
	v_and_b32_e32 v101, 0xffff0000, v87
	v_lshlrev_b32_e32 v52, 16, v91
	v_and_b32_e32 v53, 0xffff0000, v91
	v_pk_add_f32 v[100:101], v[100:101], v[52:53]
	v_lshlrev_b32_e32 v52, 16, v95
	v_and_b32_e32 v53, 0xffff0000, v95
	v_pk_mul_f32 v[100:101], v[100:101], v[52:53]
	s_nop 0
	v_cvt_pk_bf16_f32 v87, v100, v101
	global_store_dwordx4 v250, v[84:87], s[90:91]
	s_waitcnt vmcnt(5)
	v_lshlrev_b32_e32 v100, 16, v56
	v_and_b32_e32 v101, 0xffff0000, v56
	v_lshlrev_b32_e32 v52, 16, v60
	v_and_b32_e32 v53, 0xffff0000, v60
	v_pk_add_f32 v[100:101], v[100:101], v[52:53]
	v_lshlrev_b32_e32 v52, 16, v64
	v_and_b32_e32 v53, 0xffff0000, v64
	v_pk_mul_f32 v[100:101], v[100:101], v[52:53]
	s_nop 0
	v_cvt_pk_bf16_f32 v56, v100, v101
	v_lshlrev_b32_e32 v100, 16, v57
	v_and_b32_e32 v101, 0xffff0000, v57
	v_lshlrev_b32_e32 v52, 16, v61
	v_and_b32_e32 v53, 0xffff0000, v61
	v_pk_add_f32 v[100:101], v[100:101], v[52:53]
	v_lshlrev_b32_e32 v52, 16, v65
	v_and_b32_e32 v53, 0xffff0000, v65
	v_pk_mul_f32 v[100:101], v[100:101], v[52:53]
	s_nop 0
	v_cvt_pk_bf16_f32 v57, v100, v101
	v_lshlrev_b32_e32 v100, 16, v58
	v_and_b32_e32 v101, 0xffff0000, v58
	v_lshlrev_b32_e32 v52, 16, v62
	v_and_b32_e32 v53, 0xffff0000, v62
	v_pk_add_f32 v[100:101], v[100:101], v[52:53]
	v_lshlrev_b32_e32 v52, 16, v66
	v_and_b32_e32 v53, 0xffff0000, v66
	v_pk_mul_f32 v[100:101], v[100:101], v[52:53]
	s_nop 0
	v_cvt_pk_bf16_f32 v58, v100, v101
	v_lshlrev_b32_e32 v100, 16, v59
	v_and_b32_e32 v101, 0xffff0000, v59
	v_lshlrev_b32_e32 v52, 16, v63
	v_and_b32_e32 v53, 0xffff0000, v63
	v_pk_add_f32 v[100:101], v[100:101], v[52:53]
	v_lshlrev_b32_e32 v52, 16, v67
	v_and_b32_e32 v53, 0xffff0000, v67
	v_pk_mul_f32 v[100:101], v[100:101], v[52:53]
	s_nop 0
	v_cvt_pk_bf16_f32 v59, v100, v101
	global_store_dwordx4 v251, v[56:59], s[90:91]
	s_waitcnt vmcnt(3)
	v_lshlrev_b32_e32 v100, 16, v68
	v_and_b32_e32 v101, 0xffff0000, v68
	v_lshlrev_b32_e32 v52, 16, v44
	v_and_b32_e32 v53, 0xffff0000, v44
	v_pk_add_f32 v[100:101], v[100:101], v[52:53]
	v_lshlrev_b32_e32 v52, 16, v48
	v_and_b32_e32 v53, 0xffff0000, v48
	v_pk_mul_f32 v[100:101], v[100:101], v[52:53]
	s_nop 0
	v_cvt_pk_bf16_f32 v68, v100, v101
	v_lshlrev_b32_e32 v100, 16, v69
	v_and_b32_e32 v101, 0xffff0000, v69
	v_lshlrev_b32_e32 v52, 16, v45
	v_and_b32_e32 v53, 0xffff0000, v45
	v_pk_add_f32 v[100:101], v[100:101], v[52:53]
	v_lshlrev_b32_e32 v52, 16, v49
	v_and_b32_e32 v53, 0xffff0000, v49
	v_pk_mul_f32 v[100:101], v[100:101], v[52:53]
	s_nop 0
	v_cvt_pk_bf16_f32 v69, v100, v101
	v_lshlrev_b32_e32 v100, 16, v70
	v_and_b32_e32 v101, 0xffff0000, v70
	v_lshlrev_b32_e32 v52, 16, v46
	v_and_b32_e32 v53, 0xffff0000, v46
	v_pk_add_f32 v[100:101], v[100:101], v[52:53]
	v_lshlrev_b32_e32 v52, 16, v50
	v_and_b32_e32 v53, 0xffff0000, v50
	v_pk_mul_f32 v[100:101], v[100:101], v[52:53]
	s_nop 0
	v_cvt_pk_bf16_f32 v70, v100, v101
	v_lshlrev_b32_e32 v100, 16, v71
	v_and_b32_e32 v101, 0xffff0000, v71
	v_lshlrev_b32_e32 v52, 16, v47
	v_and_b32_e32 v53, 0xffff0000, v47
	v_pk_add_f32 v[100:101], v[100:101], v[52:53]
	v_lshlrev_b32_e32 v52, 16, v51
	v_and_b32_e32 v53, 0xffff0000, v51
	v_pk_mul_f32 v[100:101], v[100:101], v[52:53]
	s_nop 0
	v_cvt_pk_bf16_f32 v71, v100, v101
	global_store_dwordx4 v252, v[68:71], s[90:91]
	s_cbranch_scc1 .LBB0_30

; __device__ __forceinline__ bf16_t f2bf(float f) { return (bf16_t)(pk2(f, 0.f) & 0xffffu); }
; __device__ __forceinline__ void refresh(Frame& F) { int t = threadIdx.x; asm volatile("" : "+v"(t)); F.tid = t; F.lane = t & 63; F.wave = __builtin_amdgcn_readfirstlane(t >> 6); }
; __device__ __forceinline__ void ret_state_item(const Args& A, Frame& F, int l, int it) {
;     refresh(F);
;     const int dvh = it & 1, dir = (it >> 1) & 1, h = (it >> 2) & 7, b = it >> 5;
;     const int lane = F.lane, fr = lane & 15, fq = lane >> 4, w = F.wave, dvt = w & 3, dkh = w >> 2;
;     const float l2g = log2_gamma(A, F, l, dir, h);
;     const float cdec = exp2f(128.f * l2g);
;     float dec[4][8];
; #pragma unroll
;     for (int ks = 0; ks < 4; ++ks)
; #pragma unroll
;         for (int s = 0; s < 8; ++s) { const int a = 32 * ks + 8 * fq + s; dec[ks][s] = exp2f(l2g * (float)(dir ? a : 127 - a)); }
;     const int dvrow = 64 * dvh + 16 * dvt + fr;
;     const bf16_t* kbase = WSB(WS_KT) + ((size_t)(b * NH + h) * DK + 32 * dkh + fr) * TB;
;     const bf16_t* vbase = WSB(WS_VT) + ((size_t)(b * NH + h) * DV + dvrow) * TB;
;     f32x4 acc[2];
;     acc[0] = (f32x4){0.f, 0.f, 0.f, 0.f}; acc[1] = acc[0];
; __device__ __forceinline__ void lru_item(const Args& A, Frame& F, int l, int it) {
;     ...
;     __syncthreads();
;     {
;         const float* gw = GIN(16) + ((size_t)(l * 2 + dir) * 2) * 16 * 64 * 64;
;         for (int e = tid; e < 2 * 64 * 64; e += NTHREADS) {
;             const int g = e >> 12, k = (e >> 6) & 63, j = e & 63;
;             wgs[(g * 64 + j) * 72 + k] = f2bf(gw[((size_t)(g * 16 + blk) * 64 + k) * 64 + j]);
;         }
;         if (tid < 128) hcar[tid] = 0.f;
;     }
.LBB0_51:
	v_readfirstlane_b32 s2, v138
	s_and_b32 s8, s37, 1
	s_bfe_u32 s10, s37, 0x10001
	s_lshr_b32 s9, s37, 2
	s_and_b32 s12, s9, 7
	s_lshr_b32 s2, s2, 6
	s_lshl_b32 s13, s10, 3
	s_add_i32 s13, s13, s12
	s_add_i32 s13, s13, s53
	s_lshl_b32 s13, s13, 2
	s_load_dwordx2 s[100:101], s[46:47], 0x60
	s_waitcnt lgkmcnt(0)
	s_load_dword s5, s[100:101], s13
	s_lshr_b32 s15, s2, 2
	s_and_b32 s18, s2, 3
	s_cmp_eq_u32 s10, 0
	s_cselect_b32 s14, -1, 1
	s_waitcnt lgkmcnt(0)
	v_mov_b32_e32 v250, s5
	v_and_b32_e32 v251, 0x7fffffff, v250
	v_mul_f32_e32 v251, 0xbfb8aa3b, v251
	v_exp_f32_e32 v251, v251
	v_mov_b32_e32 v252, 0x3e4ccccd
	v_fmaak_f32 v252, v251, v252, 0xbe800000
	v_fmaak_f32 v252, v251, v252, 0x3eaaaaab
	v_fmaak_f32 v252, v251, v252, 0xbf000000
	v_fmaak_f32 v252, v251, v252, 0x3f800000
	v_mul_f32_e32 v252, v251, v252
	v_add_f32_e32 v253, 1.0, v251
	v_log_f32_e32 v253, v253
	v_cmp_gt_f32_e32 vcc, 0x3c800000, v251
	v_mul_f32_e32 v253, 0x3f317218, v253
	s_nop 1
	v_cndmask_b32_e32 v252, v253, v252, vcc
	v_max_f32_e64 v253, -v250, 0
	v_add_f32_e32 v252, v253, v252
	v_mul_f32_e32 v252, 0xbfb8aa3b, v252
	v_mul_f32_e32 v168, 0x43000000, v252
	v_exp_f32_e32 v168, v168
	v_and_b32_e32 v141, 63, v138
	v_and_b32_e32 v137, 15, v141
	v_lshrrev_b32_e32 v141, 4, v141
	s_cmp_eq_u32 s10, 0
	s_cselect_b32 s4, 0x7f, 0
	v_mov_b32_e32 v143, s14
	v_lshlrev_b32_e32 v255, 3, v141
	v_mad_i32_i24 v255, v143, v255, s4
	v_mad_i32_i24 v250, v143, 0, v255
	v_cvt_f32_i32_e32 v250, v250
	v_mul_f32_e32 v250, v252, v250
	v_exp_f32_e32 v152, v250
	v_mad_i32_i24 v250, v143, 1, v255
	v_cvt_f32_i32_e32 v250, v250
	v_mul_f32_e32 v250, v252, v250
	v_exp_f32_e32 v153, v250
	v_mad_i32_i24 v250, v143, 2, v255
	v_cvt_f32_i32_e32 v250, v250
	v_mul_f32_e32 v250, v252, v250
	v_exp_f32_e32 v154, v250
	v_mad_i32_i24 v250, v143, 3, v255
	v_cvt_f32_i32_e32 v250, v250
	v_mul_f32_e32 v250, v252, v250
	v_exp_f32_e32 v155, v250
	v_mad_i32_i24 v250, v143, 4, v255
	v_cvt_f32_i32_e32 v250, v250
	v_mul_f32_e32 v250, v252, v250
	v_exp_f32_e32 v156, v250
	v_mad_i32_i24 v250, v143, 5, v255
	v_cvt_f32_i32_e32 v250, v250
	v_mul_f32_e32 v250, v252, v250
	v_exp_f32_e32 v157, v250
	v_mad_i32_i24 v250, v143, 6, v255
	v_cvt_f32_i32_e32 v250, v250
	v_mul_f32_e32 v250, v252, v250
	v_exp_f32_e32 v158, v250
	v_mad_i32_i24 v250, v143, 7, v255
	v_cvt_f32_i32_e32 v250, v250
	v_mul_f32_e32 v250, v252, v250
	v_exp_f32_e32 v159, v250
	s_lshl_b32 s4, s14, 5
	v_cvt_f32_i32_e32 v250, s4
	v_mul_f32_e32 v250, v252, v250
	v_add_f32_e32 v251, v250, v250
	v_add_f32_e32 v253, v251, v250
	v_exp_f32_e32 v244, v250
	v_exp_f32_e32 v246, v251
	v_exp_f32_e32 v248, v253
	s_lshl_b32 s4, s9, 6
	s_lshl_b32 s5, s15, 5
	s_add_i32 s4, s4, s5
	s_mulk_i32 s4, 0x1200
	v_mul_u32_u24_e32 v169, 0x1200, v137
	v_lshl_add_u32 v169, v141, 4, v169
	v_add_u32_e32 v169, s4, v169
	s_lshl_b32 s5, s8, 6
	s_lshl_b32 s18, s18, 4
	s_add_i32 s18, s18, s5
	s_lshl_b32 s4, s9, 7
	s_add_i32 s4, s4, s18
	s_mulk_i32 s4, 0x1200
	v_mul_u32_u24_e32 v242, 0x1200, v137
	v_lshl_add_u32 v242, v141, 4, v242
	v_add_u32_e32 v242, s4, v242
	s_lshl_b32 s4, s9, 1
	s_add_i32 s4, s4, s10
	s_mulk_i32 s4, 0x900
	s_add_i32 s4, s4, s18
	s_lshl_b32 s4, s4, 7
	s_lshl_b32 s5, s15, 6
	s_add_i32 s4, s4, s5
	v_lshlrev_b32_e32 v243, 7, v137
	v_lshl_add_u32 v243, v141, 3, v243
	v_add_u32_e32 v243, s4, v243
	v_mov_b32_e32 v160, 0
	v_mov_b32_e32 v161, 0
	v_mov_b32_e32 v162, 0
	v_mov_b32_e32 v163, 0
	v_mov_b32_e32 v164, 0
	v_mov_b32_e32 v165, 0
	v_mov_b32_e32 v166, 0
	v_mov_b32_e32 v167, 0
	s_bfe_u32 s45, s37, 0x10004
	v_mov_b32_e32 v54, v138
	s_or_b32 s4, s45, s85
	s_movk_i32 s8, 0x2000
	s_and_b32 s39, s37, 15
	v_and_b32_e32 v102, 63, v54
	v_readfirstlane_b32 s2, v54
	s_ashr_i32 s5, s4, 31
	v_cmp_gt_i32_e32 vcc, s8, v54
	s_barrier
	s_and_saveexec_b64 s[8:9], vcc
	s_mov_b32 s18, 0x33800000
	s_mov_b32 s19, 0x3f317218
	s_cbranch_execz .LBB0_59
	s_load_dwordx2 s[10:11], s[46:47], 0x80
	s_lshl_b64 s[12:13], s[4:5], 19
	v_lshrrev_b32_e32 v141, 6, v54
	v_lshlrev_b32_e32 v137, 8, v141
	v_lshl_add_u32 v137, v102, 2, v137
	v_mul_u32_u24_e32 v0, 0x90, v102
	v_lshl_add_u32 v141, v141, 1, v0
	v_add_u32_e32 v141, 0x14800, v141
	s_waitcnt lgkmcnt(0)
	s_add_u32 s10, s10, s12
	s_addc_u32 s11, s11, s13
	s_lshl_b32 s12, s39, 14
	s_add_u32 s10, s10, s12
	s_addc_u32 s11, s11, 0
	s_waitcnt vmcnt(0)
	global_load_dword v2, v137, s[10:11]
	s_add_u32 s100, s10, 0x800
	s_addc_u32 s101, s11, 0
	global_load_dword v3, v137, s[100:101]
	s_add_u32 s98, s10, 0x1000
	s_addc_u32 s99, s11, 0
	global_load_dword v4, v137, s[98:99]
	s_add_u32 s100, s10, 0x1800
	s_addc_u32 s101, s11, 0
	global_load_dword v5, v137, s[100:101]
	s_add_u32 s98, s10, 0x2000
	s_addc_u32 s99, s11, 0
	global_load_dword v6, v137, s[98:99]
	s_add_u32 s100, s10, 0x2800
	s_addc_u32 s101, s11, 0
	global_load_dword v7, v137, s[100:101]
	s_add_u32 s98, s10, 0x3000
	s_addc_u32 s99, s11, 0
	global_load_dword v8, v137, s[98:99]
	s_add_u32 s100, s10, 0x3800
	s_addc_u32 s101, s11, 0
	global_load_dword v9, v137, s[100:101]
	s_add_u32 s98, s10, 0x40000
	s_addc_u32 s99, s11, 0
	global_load_dword v10, v137, s[98:99]
	s_add_u32 s100, s10, 0x40800
	s_addc_u32 s101, s11, 0
	global_load_dword v11, v137, s[100:101]
	s_add_u32 s98, s10, 0x41000
	s_addc_u32 s99, s11, 0
	global_load_dword v12, v137, s[98:99]
	s_add_u32 s100, s10, 0x41800
	s_addc_u32 s101, s11, 0
	global_load_dword v13, v137, s[100:101]
	s_add_u32 s98, s10, 0x42000
	s_addc_u32 s99, s11, 0
	global_load_dword v14, v137, s[98:99]
	s_add_u32 s100, s10, 0x42800
	s_addc_u32 s101, s11, 0
	global_load_dword v15, v137, s[100:101]
	s_add_u32 s98, s10, 0x43000
	s_addc_u32 s99, s11, 0
	global_load_dword v143, v137, s[98:99]
	s_add_u32 s100, s10, 0x43800
	s_addc_u32 s101, s11, 0
	global_load_dword v255, v137, s[100:101]
	s_waitcnt vmcnt(14)
	v_cvt_pk_bf16_f32 v2, v2, v3
	ds_write_b16 v141, v2
	ds_write_b16_d16_hi v141, v2 offset:16
	s_waitcnt vmcnt(12)
	v_cvt_pk_bf16_f32 v4, v4, v5
	ds_write_b16 v141, v4 offset:32
	ds_write_b16_d16_hi v141, v4 offset:48
	s_waitcnt vmcnt(10)
	v_cvt_pk_bf16_f32 v6, v6, v7
	ds_write_b16 v141, v6 offset:64
	ds_write_b16_d16_hi v141, v6 offset:80
	s_waitcnt vmcnt(8)
	v_cvt_pk_bf16_f32 v8, v8, v9
	ds_write_b16 v141, v8 offset:96
	ds_write_b16_d16_hi v141, v8 offset:112
	s_waitcnt vmcnt(6)
	v_cvt_pk_bf16_f32 v10, v10, v11
	ds_write_b16 v141, v10 offset:9216
	ds_write_b16_d16_hi v141, v10 offset:9232
	s_waitcnt vmcnt(4)
	v_cvt_pk_bf16_f32 v12, v12, v13
	ds_write_b16 v141, v12 offset:9248
	ds_write_b16_d16_hi v141, v12 offset:9264
	s_waitcnt vmcnt(2)
	v_cvt_pk_bf16_f32 v14, v14, v15
	ds_write_b16 v141, v14 offset:9280
	ds_write_b16_d16_hi v141, v14 offset:9296
	s_waitcnt vmcnt(0)
	v_cvt_pk_bf16_f32 v143, v143, v255
	ds_write_b16 v141, v143 offset:9312
	ds_write_b16_d16_hi v141, v143 offset:9328
	s_mov_b32 s53, s64
